# P7: SwiGLU epilogue of non-last tiles deferred into the next tile's first K-iteration load phases (no ALIGN barriers)
# baseline (speedup 1.0000x reference)
;     __host__ __device__ bool next(int i, Unit& u) const {
;         const long L = (long)i * G + c; if (L >= nwg) return false;
;         int wgid = (int)L; { const int q = nwg / NXCD, r = nwg % NXCD, xcd = wgid % NXCD, off = wgid / NXCD; wgid = (xcd < r ? xcd * (q + 1) : r * (q + 1) + (xcd - r) * q) + off; }
;         const int nig = WGM * nN, gid = wgid / nig, fm = gid * WGM, gsz = (nM - fm) < WGM ? (nM - fm) : WGM;
;         u.pm = fm + ((wgid % nig) % gsz); u.pn = (wgid % nig) / gsz; return true;
;     }
; template <class Epi, class Sched, bool ALIGN_EPI = false, bool SP2 = false>
; __device__ __forceinline__ void gemm_phase(PG8_LAS unsigned char* lds, const Gemm g, const Sched& S, const Epi& E) {
;     ...
; #pragma unroll
;         for (int a = 0; a < 2; ++a)
; #pragma unroll
;             for (int b = 0; b < 2; ++b)
; #pragma unroll
;                 for (int m = 0; m < 4; ++m)
; #pragma unroll
;                     for (int n = 0; n < 2; ++n) acc[a][b][m][n] = (f32x4){0.f, 0.f, 0.f, 0.f};
;         cur = nxt; cA = nA; cB = nB; ++ui;
.LBB0_602:
	s_add_i32 s37, s37, 1
	s_mul_i32 s2, s37, s46
	s_mul_hi_u32 s3, s37, s47
	s_add_i32 s3, s3, s2
	s_mul_i32 s2, s37, s47
	s_add_u32 s14, s2, s26
	s_addc_u32 s15, s3, s23
	v_cmp_gt_i64_e32 vcc, s[14:15], v[142:143]
	v_cmp_lt_i64_e64 s[2:3], s[14:15], v[140:141]
	s_cbranch_vccnz .LBB0_604
	s_ashr_i32 s10, s14, 31
	s_lshr_b32 s10, s10, 29
	s_add_i32 s10, s14, s10
	s_ashr_i32 s11, s10, 3
	s_and_b32 s10, s10, -8
	s_sub_i32 s10, s14, s10
	s_cmp_lt_i32 s10, 0
	s_cselect_b32 s12, s28, 0x2c0
	s_mul_i32 s10, s10, s12
	s_add_i32 s10, s10, s11
	s_mul_hi_i32 s11, s10, 0x2e8ba2e9
	s_lshr_b32 s12, s11, 31
	s_ashr_i32 s11, s11, 5
	s_add_i32 s11, s11, s12
	s_lshl_b32 s12, s11, 3
	s_sub_i32 s13, 0x100, s12
	s_min_i32 s13, s13, 8
	s_abs_i32 s14, s13
	v_cvt_f32_u32_e32 v236, s14
	s_sub_i32 s16, 0, s14
	s_mulk_i32 s11, 0xb0
	s_sub_i32 s11, s10, s11
	v_rcp_iflag_f32_e32 v236, v236
	s_abs_i32 s10, s11
	s_xor_b32 s15, s11, s13
	s_ashr_i32 s15, s15, 31
	v_mul_f32_e32 v236, 0x4f7ffffe, v236
	v_cvt_u32_f32_e32 v236, v236
	s_nop 0
	v_readfirstlane_b32 s17, v236
	s_mul_i32 s16, s16, s17
	s_mul_hi_u32 s16, s17, s16
	s_add_i32 s17, s17, s16
	s_mul_hi_u32 s16, s10, s17
	s_mul_i32 s17, s16, s14
	s_sub_i32 s10, s10, s17
	s_add_i32 s33, s16, 1
	s_sub_i32 s17, s10, s14
	s_cmp_ge_u32 s10, s14
	s_cselect_b32 s16, s33, s16
	s_cselect_b32 s10, s17, s10
	s_add_i32 s17, s16, 1
	s_cmp_ge_u32 s10, s14
	s_cselect_b32 s10, s17, s16
	s_xor_b32 s10, s10, s15
	s_sub_i32 s10, s10, s15
	s_mul_i32 s13, s10, s13
	s_sub_i32 s11, s11, s13
	s_add_i32 s12, s12, s11
.LBB0_604:
	s_ashr_i32 s13, s12, 31
	s_lshl_b64 s[14:15], s[12:13], 19
	s_add_u32 s14, s24, s14
	s_addc_u32 s15, s25, s15
	s_and_b64 s[16:17], s[2:3], exec
	s_cselect_b32 s13, s15, s39
	s_cselect_b32 s52, s14, s38
	s_ashr_i32 s11, s10, 31
	s_lshl_b64 s[16:17], s[10:11], 19
	s_add_u32 s16, s60, s16
	s_addc_u32 s17, s61, s17
	s_and_b64 s[42:43], s[2:3], exec
	s_cselect_b32 s11, s17, s41
	s_cselect_b32 s53, s16, s40
	s_add_u32 s38, s38, 0x40080
	s_addc_u32 s39, s39, 0
	s_add_u32 s54, s40, 0x100
	s_addc_u32 s55, s41, 0
	s_mov_b32 s56, -2
	s_cmp_lg_u32 s37, 1
	s_cbranch_scc1 .Lpeel_p7
	v_mov_b32_e32 v0, 0
	v_mov_b32_e32 v1, v0
	v_mov_b32_e32 v2, v0
	v_mov_b32_e32 v3, v0
	v_mov_b32_e32 v4, v0
	v_mov_b32_e32 v5, v0
	v_mov_b32_e32 v6, v0
	v_mov_b32_e32 v7, v0
	v_mov_b32_e32 v16, v0
	v_mov_b32_e32 v17, v0
	v_mov_b32_e32 v18, v0
	v_mov_b32_e32 v19, v0
	v_mov_b32_e32 v20, v0
	v_mov_b32_e32 v21, v0
	v_mov_b32_e32 v22, v0
	v_mov_b32_e32 v23, v0
	v_mov_b32_e32 v32, v0
	v_mov_b32_e32 v33, v0
	v_mov_b32_e32 v34, v0
	v_mov_b32_e32 v35, v0
	v_mov_b32_e32 v36, v0
	v_mov_b32_e32 v37, v0
	v_mov_b32_e32 v38, v0
	v_mov_b32_e32 v39, v0
	v_mov_b32_e32 v48, v0
	v_mov_b32_e32 v49, v0
	v_mov_b32_e32 v50, v0
	v_mov_b32_e32 v51, v0
	v_mov_b32_e32 v52, v0
	v_mov_b32_e32 v53, v0
	v_mov_b32_e32 v54, v0
	v_mov_b32_e32 v55, v0
	v_mov_b32_e32 v8, v0
	v_mov_b32_e32 v9, v0
	v_mov_b32_e32 v10, v0
	v_mov_b32_e32 v11, v0
	v_mov_b32_e32 v12, v0
	v_mov_b32_e32 v13, v0
	v_mov_b32_e32 v14, v0
	v_mov_b32_e32 v15, v0
	v_mov_b32_e32 v24, v0
	v_mov_b32_e32 v25, v0
	v_mov_b32_e32 v26, v0
	v_mov_b32_e32 v27, v0
	v_mov_b32_e32 v28, v0
	v_mov_b32_e32 v29, v0
	v_mov_b32_e32 v30, v0
	v_mov_b32_e32 v31, v0
	v_mov_b32_e32 v40, v0
	v_mov_b32_e32 v41, v0
	v_mov_b32_e32 v42, v0
	v_mov_b32_e32 v43, v0
	v_mov_b32_e32 v44, v0
	v_mov_b32_e32 v45, v0
	v_mov_b32_e32 v46, v0
	v_mov_b32_e32 v47, v0
	v_mov_b32_e32 v56, v0
	v_mov_b32_e32 v57, v0
	v_mov_b32_e32 v58, v0
	v_mov_b32_e32 v59, v0
	v_mov_b32_e32 v60, v0
	v_mov_b32_e32 v61, v0
	v_mov_b32_e32 v62, v0
	v_mov_b32_e32 v63, v0
	v_mov_b32_e32 v64, v0
	v_mov_b32_e32 v65, v0
	v_mov_b32_e32 v66, v0
	v_mov_b32_e32 v67, v0
	v_mov_b32_e32 v68, v0
	v_mov_b32_e32 v69, v0
	v_mov_b32_e32 v70, v0
	v_mov_b32_e32 v71, v0
	v_mov_b32_e32 v80, v0
	v_mov_b32_e32 v81, v0
	v_mov_b32_e32 v82, v0
	v_mov_b32_e32 v83, v0
	v_mov_b32_e32 v84, v0
	v_mov_b32_e32 v85, v0
	v_mov_b32_e32 v86, v0
	v_mov_b32_e32 v87, v0
	v_mov_b32_e32 v96, v0
	v_mov_b32_e32 v97, v0
	v_mov_b32_e32 v98, v0
	v_mov_b32_e32 v99, v0
	v_mov_b32_e32 v100, v0
	v_mov_b32_e32 v101, v0
	v_mov_b32_e32 v102, v0
	v_mov_b32_e32 v103, v0
	v_mov_b32_e32 v112, v0
	v_mov_b32_e32 v113, v0
	v_mov_b32_e32 v114, v0
	v_mov_b32_e32 v115, v0
	v_mov_b32_e32 v116, v0
	v_mov_b32_e32 v117, v0
	v_mov_b32_e32 v118, v0
	v_mov_b32_e32 v119, v0
	v_mov_b32_e32 v72, v0
	v_mov_b32_e32 v73, v0
	v_mov_b32_e32 v74, v0
	v_mov_b32_e32 v75, v0
	v_mov_b32_e32 v76, v0
	v_mov_b32_e32 v77, v0
	v_mov_b32_e32 v78, v0
	v_mov_b32_e32 v79, v0
	v_mov_b32_e32 v88, v0
	v_mov_b32_e32 v89, v0
	v_mov_b32_e32 v90, v0
	v_mov_b32_e32 v91, v0
	v_mov_b32_e32 v92, v0
	v_mov_b32_e32 v93, v0
	v_mov_b32_e32 v94, v0
	v_mov_b32_e32 v95, v0
	v_mov_b32_e32 v104, v0
	v_mov_b32_e32 v105, v0
	v_mov_b32_e32 v106, v0
	v_mov_b32_e32 v107, v0
	v_mov_b32_e32 v108, v0
	v_mov_b32_e32 v109, v0
	v_mov_b32_e32 v110, v0
	v_mov_b32_e32 v111, v0
	v_mov_b32_e32 v120, v0
	v_mov_b32_e32 v121, v0
	v_mov_b32_e32 v122, v0
	v_mov_b32_e32 v123, v0
	v_mov_b32_e32 v124, v0
	v_mov_b32_e32 v125, v0
	v_mov_b32_e32 v126, v0
	v_mov_b32_e32 v127, v0
; #define PG8_STAGE(bufoff, gbase, voff) do { _Pragma("unroll") for (int _i = 0; _i < 2; ++_i) \
;         __builtin_amdgcn_global_load_lds((const unsigned*)((const char*)(gbase) + (voff)[_i]), (PG8_LAS unsigned*)(lds + (bufoff) + ldsw + _i * 8192), 16, 0, 0); } while (0)
; #define PG8_LDA(dst, b, h) do { _Pragma("unroll") for (int m = 0; m < 4; ++m) _Pragma("unroll") for (int k = 0; k < 2; ++k) dst[m][k] = *(const PG8_LAS bf16x8*)(lds + PG8_SA(b, h) + aoff + m * 2048 + k * 1024); } while (0)
; #define PG8_LDB(dst, b, h) do { _Pragma("unroll") for (int n = 0; n < 2; ++n) _Pragma("unroll") for (int k = 0; k < 2; ++k) dst[n][k] = *(const PG8_LAS bf16x8*)(lds + PG8_SB(b, h) + boff + n * 2048 + k * 1024); } while (0)
; #define PG8_MMA(ai, bj, At, Bt) do { __builtin_amdgcn_s_setprio(1); _Pragma("unroll") for (int m = 0; m < 4; ++m) _Pragma("unroll") for (int n = 0; n < 2; ++n) _Pragma("unroll") for (int k = 0; k < 2; ++k) \
;         acc[ai][bj][m][n] = __builtin_amdgcn_mfma_f32_16x16x32_bf16(Bt[n][k], At[m][k], acc[ai][bj][m][n], 0, 0, 0); __builtin_amdgcn_s_setprio(0); } while (0)
; #define PG8_WAIT_V(n) asm volatile("s_waitcnt vmcnt(" #n ")" ::: "memory")
; #define PG8_WAIT_L(n) asm volatile("s_waitcnt lgkmcnt(" #n ")" ::: "memory")
; #define PG8_BAR __builtin_amdgcn_s_barrier()
; #define PG8_SCHED __builtin_amdgcn_sched_barrier(0)
; template <class Epi, class Sched, bool ALIGN_EPI = false, bool SP2 = false>
; __device__ __forceinline__ void gemm_phase(PG8_LAS unsigned char* lds, const Gemm g, const Sched& S, const Epi& E) {
;     ...
;             PG8_LDB(B0, 0, 0); PG8_LDB(B1, 0, 1); PG8_SCHED; PG8_LDA(At, 0, 0); PG8_STAGE(PG8_SA(1, 1), a1 + hstepA, voffA);
;             PG8_WAIT_V(8); PG8_WAIT_L(0); PG8_BAR; PG8_MMA(0, 0, At, B0); PG8_MMA(0, 1, At, B1); PG8_BAR; PG8_SCHED;
;             PG8_LDA(At, 0, 1); PG8_STAGE(PG8_SB(0, 0), b2, voffB); PG8_STAGE(PG8_SB(0, 1), b2 + hstepB, voffB); PG8_STAGE(PG8_SA(0, 0), a2, voffA);
;             PG8_WAIT_V(8); PG8_WAIT_L(0); PG8_BAR; PG8_MMA(1, 0, At, B0); PG8_MMA(1, 1, At, B1); PG8_BAR; PG8_SCHED;
.LBB0_605:
	ds_read_b128 v[144:147], v151
	ds_read_b128 v[154:157], v151 offset:1024
	ds_read_b128 v[158:161], v151 offset:2048
	ds_read_b128 v[162:165], v151 offset:3072
	ds_read_b128 v[166:169], v152
	ds_read_b128 v[170:173], v152 offset:1024
	ds_read_b128 v[176:179], v152 offset:2048
	ds_read_b128 v[180:183], v152 offset:3072
	s_add_u32 s33, s38, 0xfffc0080
	s_addc_u32 s40, s39, -1
	s_cmp_eq_u32 s56, 12
	s_cselect_b32 s43, s13, s40
	s_cselect_b32 s42, s52, s33
	s_cselect_b32 s41, s11, s55
	s_cselect_b32 s40, s53, s54
	v_lshl_add_u64 v[216:217], s[38:39], 0, v[136:137]
	s_add_i32 m0, s29, 0xc000
	ds_read_b128 v[184:187], v153
	ds_read_b128 v[188:191], v153 offset:1024
	ds_read_b128 v[192:195], v153 offset:2048
	ds_read_b128 v[196:199], v153 offset:3072
	ds_read_b128 v[200:203], v153 offset:4096
	ds_read_b128 v[204:207], v153 offset:5120
	ds_read_b128 v[208:211], v153 offset:6144
	ds_read_b128 v[212:215], v153 offset:7168
	global_load_lds_dwordx4 v[216:217], off
	v_lshl_add_u64 v[216:217], s[38:39], 0, v[138:139]
	s_add_i32 m0, s29, 0xe000
	s_nop 0
	global_load_lds_dwordx4 v[216:217], off
	s_waitcnt vmcnt(8)
	s_waitcnt lgkmcnt(0)
	s_barrier
	s_setprio 1
	s_waitcnt lgkmcnt(0)
	v_mfma_f32_16x16x32_bf16 v[124:127], v[144:147], v[184:187], v[124:127]
	v_mfma_f32_16x16x32_bf16 v[120:123], v[158:161], v[184:187], v[120:123]
	v_mfma_f32_16x16x32_bf16 v[108:111], v[144:147], v[192:195], v[108:111]
	v_mfma_f32_16x16x32_bf16 v[104:107], v[158:161], v[192:195], v[104:107]
	v_mfma_f32_16x16x32_bf16 v[92:95], v[144:147], v[200:203], v[92:95]
	v_mfma_f32_16x16x32_bf16 v[88:91], v[158:161], v[200:203], v[88:91]
	v_mfma_f32_16x16x32_bf16 v[76:79], v[144:147], v[208:211], v[76:79]
	v_mfma_f32_16x16x32_bf16 v[72:75], v[158:161], v[208:211], v[72:75]
	v_mfma_f32_16x16x32_bf16 v[124:127], v[154:157], v[188:191], v[124:127]
	v_mfma_f32_16x16x32_bf16 v[120:123], v[162:165], v[188:191], v[120:123]
	v_mfma_f32_16x16x32_bf16 v[108:111], v[154:157], v[196:199], v[108:111]
	v_mfma_f32_16x16x32_bf16 v[104:107], v[162:165], v[196:199], v[104:107]
	v_mfma_f32_16x16x32_bf16 v[92:95], v[154:157], v[204:207], v[92:95]
	v_mfma_f32_16x16x32_bf16 v[88:91], v[162:165], v[204:207], v[88:91]
	v_mfma_f32_16x16x32_bf16 v[76:79], v[154:157], v[212:215], v[76:79]
	v_mfma_f32_16x16x32_bf16 v[72:75], v[162:165], v[212:215], v[72:75]
	s_setprio 0
	s_setprio 1
	v_mfma_f32_16x16x32_bf16 v[116:119], v[166:169], v[184:187], v[116:119]
	v_mfma_f32_16x16x32_bf16 v[112:115], v[176:179], v[184:187], v[112:115]
	v_mfma_f32_16x16x32_bf16 v[100:103], v[166:169], v[192:195], v[100:103]
	v_mfma_f32_16x16x32_bf16 v[96:99], v[176:179], v[192:195], v[96:99]
	v_mfma_f32_16x16x32_bf16 v[84:87], v[166:169], v[200:203], v[84:87]
	v_mfma_f32_16x16x32_bf16 v[80:83], v[176:179], v[200:203], v[80:83]
	v_mfma_f32_16x16x32_bf16 v[68:71], v[166:169], v[208:211], v[68:71]
	v_mfma_f32_16x16x32_bf16 v[64:67], v[176:179], v[208:211], v[64:67]
	v_mfma_f32_16x16x32_bf16 v[116:119], v[170:173], v[188:191], v[116:119]
	v_mfma_f32_16x16x32_bf16 v[112:115], v[180:183], v[188:191], v[112:115]
	v_mfma_f32_16x16x32_bf16 v[100:103], v[170:173], v[196:199], v[100:103]
	v_mfma_f32_16x16x32_bf16 v[96:99], v[180:183], v[196:199], v[96:99]
	v_mfma_f32_16x16x32_bf16 v[84:87], v[170:173], v[204:207], v[84:87]
	v_mfma_f32_16x16x32_bf16 v[80:83], v[180:183], v[204:207], v[80:83]
	v_mfma_f32_16x16x32_bf16 v[68:71], v[170:173], v[212:215], v[68:71]
	v_mfma_f32_16x16x32_bf16 v[64:67], v[180:183], v[212:215], v[64:67]
	s_setprio 0
	s_barrier
	s_add_i32 s33, s48, s22
	v_lshl_add_u64 v[216:217], s[40:41], 0, v[132:133]
	s_mov_b32 m0, s33
	ds_read_b128 v[184:187], v153 offset:16384
	ds_read_b128 v[188:191], v153 offset:17408
	ds_read_b128 v[192:195], v153 offset:18432
	ds_read_b128 v[196:199], v153 offset:19456
	ds_read_b128 v[200:203], v153 offset:20480
	ds_read_b128 v[204:207], v153 offset:21504
	ds_read_b128 v[208:211], v153 offset:22528
	ds_read_b128 v[212:215], v153 offset:23552
	global_load_lds_dwordx4 v[216:217], off
	s_add_i32 m0, s33, 0x2000
	s_add_u32 s58, s40, 0x40000
	v_lshl_add_u64 v[218:219], s[40:41], 0, v[128:129]
	s_addc_u32 s59, s41, 0
	s_add_i32 s33, s49, s22
	global_load_lds_dwordx4 v[218:219], off
	v_lshl_add_u64 v[220:221], s[58:59], 0, v[132:133]
	s_mov_b32 m0, s33
	v_lshl_add_u64 v[222:223], s[42:43], 0, v[130:131]
	global_load_lds_dwordx4 v[220:221], off
	v_lshl_add_u64 v[220:221], s[58:59], 0, v[128:129]
	s_add_i32 m0, s33, 0x2000
	s_nop 0
	global_load_lds_dwordx4 v[220:221], off
	v_lshl_add_u64 v[220:221], s[42:43], 0, v[134:135]
	s_mov_b32 m0, s29
	s_nop 0
	global_load_lds_dwordx4 v[220:221], off
	s_mov_b32 m0, s30
	s_nop 0
	global_load_lds_dwordx4 v[222:223], off
	s_waitcnt vmcnt(8)
	s_waitcnt lgkmcnt(0)
	s_barrier
; #define PG8_STAGE(bufoff, gbase, voff) do { _Pragma("unroll") for (int _i = 0; _i < 2; ++_i) \
;         __builtin_amdgcn_global_load_lds((const unsigned*)((const char*)(gbase) + (voff)[_i]), (PG8_LAS unsigned*)(lds + (bufoff) + ldsw + _i * 8192), 16, 0, 0); } while (0)
; #define PG8_LDA(dst, b, h) do { _Pragma("unroll") for (int m = 0; m < 4; ++m) _Pragma("unroll") for (int k = 0; k < 2; ++k) dst[m][k] = *(const PG8_LAS bf16x8*)(lds + PG8_SA(b, h) + aoff + m * 2048 + k * 1024); } while (0)
; #define PG8_LDB(dst, b, h) do { _Pragma("unroll") for (int n = 0; n < 2; ++n) _Pragma("unroll") for (int k = 0; k < 2; ++k) dst[n][k] = *(const PG8_LAS bf16x8*)(lds + PG8_SB(b, h) + boff + n * 2048 + k * 1024); } while (0)
; #define PG8_MMA(ai, bj, At, Bt) do { __builtin_amdgcn_s_setprio(1); _Pragma("unroll") for (int m = 0; m < 4; ++m) _Pragma("unroll") for (int n = 0; n < 2; ++n) _Pragma("unroll") for (int k = 0; k < 2; ++k) \
;         acc[ai][bj][m][n] = __builtin_amdgcn_mfma_f32_16x16x32_bf16(Bt[n][k], At[m][k], acc[ai][bj][m][n], 0, 0, 0); __builtin_amdgcn_s_setprio(0); } while (0)
; #define PG8_WAIT_V(n) asm volatile("s_waitcnt vmcnt(" #n ")" ::: "memory")
; #define PG8_WAIT_L(n) asm volatile("s_waitcnt lgkmcnt(" #n ")" ::: "memory")
; #define PG8_BAR __builtin_amdgcn_s_barrier()
; #define PG8_SCHED __builtin_amdgcn_sched_barrier(0)
; template <class Epi, class Sched, bool ALIGN_EPI = false, bool SP2 = false>
; __device__ __forceinline__ void gemm_phase(PG8_LAS unsigned char* lds, const Gemm g, const Sched& S, const Epi& E) {
;     ...
;             PG8_WAIT_V(8); PG8_WAIT_L(0); PG8_BAR; PG8_MMA(1, 0, At, B0); PG8_MMA(1, 1, At, B1); PG8_BAR; PG8_SCHED;
;             PG8_LDB(B0, 1, 0); PG8_LDB(B1, 1, 1); PG8_SCHED; PG8_LDA(At, 1, 0); PG8_STAGE(PG8_SA(0, 1), a2 + hstepA, voffA);
;             PG8_WAIT_V(8); PG8_WAIT_L(0); PG8_BAR; PG8_MMA(0, 0, At, B0); PG8_MMA(0, 1, At, B1); PG8_BAR; PG8_SCHED;
;             PG8_LDA(At, 1, 1); PG8_STAGE(PG8_SB(1, 0), b3, voffB); PG8_STAGE(PG8_SB(1, 1), b3 + hstepB, voffB); PG8_STAGE(PG8_SA(1, 0), a3, voffA);
	s_setprio 1
	s_waitcnt lgkmcnt(0)
	v_mfma_f32_16x16x32_bf16 v[60:63], v[144:147], v[184:187], v[60:63]
	v_mfma_f32_16x16x32_bf16 v[56:59], v[158:161], v[184:187], v[56:59]
	v_mfma_f32_16x16x32_bf16 v[44:47], v[144:147], v[192:195], v[44:47]
	v_mfma_f32_16x16x32_bf16 v[40:43], v[158:161], v[192:195], v[40:43]
	v_mfma_f32_16x16x32_bf16 v[28:31], v[144:147], v[200:203], v[28:31]
	v_mfma_f32_16x16x32_bf16 v[24:27], v[158:161], v[200:203], v[24:27]
	v_mfma_f32_16x16x32_bf16 v[12:15], v[144:147], v[208:211], v[12:15]
	v_mfma_f32_16x16x32_bf16 v[8:11], v[158:161], v[208:211], v[8:11]
	v_mfma_f32_16x16x32_bf16 v[60:63], v[154:157], v[188:191], v[60:63]
	v_mfma_f32_16x16x32_bf16 v[56:59], v[162:165], v[188:191], v[56:59]
	v_mfma_f32_16x16x32_bf16 v[44:47], v[154:157], v[196:199], v[44:47]
	v_mfma_f32_16x16x32_bf16 v[40:43], v[162:165], v[196:199], v[40:43]
	v_mfma_f32_16x16x32_bf16 v[28:31], v[154:157], v[204:207], v[28:31]
	v_mfma_f32_16x16x32_bf16 v[24:27], v[162:165], v[204:207], v[24:27]
	v_mfma_f32_16x16x32_bf16 v[12:15], v[154:157], v[212:215], v[12:15]
	v_mfma_f32_16x16x32_bf16 v[8:11], v[162:165], v[212:215], v[8:11]
	s_setprio 0
	s_setprio 1
	v_mfma_f32_16x16x32_bf16 v[52:55], v[166:169], v[184:187], v[52:55]
	v_mfma_f32_16x16x32_bf16 v[48:51], v[176:179], v[184:187], v[48:51]
	v_mfma_f32_16x16x32_bf16 v[36:39], v[166:169], v[192:195], v[36:39]
	v_mfma_f32_16x16x32_bf16 v[32:35], v[176:179], v[192:195], v[32:35]
	v_mfma_f32_16x16x32_bf16 v[20:23], v[166:169], v[200:203], v[20:23]
	v_mfma_f32_16x16x32_bf16 v[16:19], v[176:179], v[200:203], v[16:19]
	v_mfma_f32_16x16x32_bf16 v[4:7], v[166:169], v[208:211], v[4:7]
	v_mfma_f32_16x16x32_bf16 v[0:3], v[176:179], v[208:211], v[0:3]
	v_mfma_f32_16x16x32_bf16 v[52:55], v[170:173], v[188:191], v[52:55]
	v_mfma_f32_16x16x32_bf16 v[48:51], v[180:183], v[188:191], v[48:51]
	v_mfma_f32_16x16x32_bf16 v[36:39], v[170:173], v[196:199], v[36:39]
	v_mfma_f32_16x16x32_bf16 v[32:35], v[180:183], v[196:199], v[32:35]
	v_mfma_f32_16x16x32_bf16 v[20:23], v[170:173], v[204:207], v[20:23]
	v_mfma_f32_16x16x32_bf16 v[16:19], v[180:183], v[204:207], v[16:19]
	v_mfma_f32_16x16x32_bf16 v[4:7], v[170:173], v[212:215], v[4:7]
	v_mfma_f32_16x16x32_bf16 v[0:3], v[180:183], v[212:215], v[0:3]
	s_setprio 0
	s_barrier
	s_add_i32 s33, 0, 0x18000
	s_add_i32 s57, 0, 0x1c000
	v_add_u32_e32 v162, s33, v149
	v_add_u32_e32 v175, s57, v149
	ds_read_b128 v[144:147], v162
	ds_read_b128 v[154:157], v162 offset:1024
	ds_read_b128 v[158:161], v162 offset:2048
	ds_read_b128 v[162:165], v162 offset:3072
	ds_read_b128 v[166:169], v175
	ds_read_b128 v[170:173], v175 offset:1024
	ds_read_b128 v[176:179], v175 offset:2048
	ds_read_b128 v[180:183], v175 offset:3072
	s_add_u32 s42, s42, 0x40000
	s_addc_u32 s43, s43, 0
	s_mov_b32 m0, s31
	v_lshl_add_u64 v[224:225], s[42:43], 0, v[134:135]
	ds_read_b128 v[184:187], v153 offset:32768
	ds_read_b128 v[188:191], v153 offset:33792
	ds_read_b128 v[192:195], v153 offset:34816
	ds_read_b128 v[196:199], v153 offset:35840
	ds_read_b128 v[200:203], v153 offset:36864
	ds_read_b128 v[204:207], v153 offset:37888
	ds_read_b128 v[208:211], v153 offset:38912
	ds_read_b128 v[212:215], v153 offset:39936
	global_load_lds_dwordx4 v[224:225], off
	v_lshl_add_u64 v[224:225], s[42:43], 0, v[130:131]
	s_mov_b32 m0, s35
	s_nop 0
	global_load_lds_dwordx4 v[224:225], off
	s_waitcnt vmcnt(8)
	s_waitcnt lgkmcnt(0)
	s_barrier
	s_setprio 1
	s_waitcnt lgkmcnt(0)
	v_mfma_f32_16x16x32_bf16 v[124:127], v[144:147], v[184:187], v[124:127]
	v_mfma_f32_16x16x32_bf16 v[120:123], v[158:161], v[184:187], v[120:123]
	v_mfma_f32_16x16x32_bf16 v[108:111], v[144:147], v[192:195], v[108:111]
	v_mfma_f32_16x16x32_bf16 v[104:107], v[158:161], v[192:195], v[104:107]
	v_mfma_f32_16x16x32_bf16 v[92:95], v[144:147], v[200:203], v[92:95]
	v_mfma_f32_16x16x32_bf16 v[88:91], v[158:161], v[200:203], v[88:91]
	v_mfma_f32_16x16x32_bf16 v[76:79], v[144:147], v[208:211], v[76:79]
	v_mfma_f32_16x16x32_bf16 v[72:75], v[158:161], v[208:211], v[72:75]
	v_mfma_f32_16x16x32_bf16 v[124:127], v[154:157], v[188:191], v[124:127]
	v_mfma_f32_16x16x32_bf16 v[120:123], v[162:165], v[188:191], v[120:123]
	v_mfma_f32_16x16x32_bf16 v[108:111], v[154:157], v[196:199], v[108:111]
	v_mfma_f32_16x16x32_bf16 v[104:107], v[162:165], v[196:199], v[104:107]
	v_mfma_f32_16x16x32_bf16 v[92:95], v[154:157], v[204:207], v[92:95]
	v_mfma_f32_16x16x32_bf16 v[88:91], v[162:165], v[204:207], v[88:91]
	v_mfma_f32_16x16x32_bf16 v[76:79], v[154:157], v[212:215], v[76:79]
	v_mfma_f32_16x16x32_bf16 v[72:75], v[162:165], v[212:215], v[72:75]
	s_setprio 0
	s_setprio 1
	v_mfma_f32_16x16x32_bf16 v[116:119], v[166:169], v[184:187], v[116:119]
	v_mfma_f32_16x16x32_bf16 v[112:115], v[176:179], v[184:187], v[112:115]
	v_mfma_f32_16x16x32_bf16 v[100:103], v[166:169], v[192:195], v[100:103]
	v_mfma_f32_16x16x32_bf16 v[96:99], v[176:179], v[192:195], v[96:99]
	v_mfma_f32_16x16x32_bf16 v[84:87], v[166:169], v[200:203], v[84:87]
	v_mfma_f32_16x16x32_bf16 v[80:83], v[176:179], v[200:203], v[80:83]
	v_mfma_f32_16x16x32_bf16 v[68:71], v[166:169], v[208:211], v[68:71]
	v_mfma_f32_16x16x32_bf16 v[64:67], v[176:179], v[208:211], v[64:67]
	v_mfma_f32_16x16x32_bf16 v[116:119], v[170:173], v[188:191], v[116:119]
	v_mfma_f32_16x16x32_bf16 v[112:115], v[180:183], v[188:191], v[112:115]
	v_mfma_f32_16x16x32_bf16 v[100:103], v[170:173], v[196:199], v[100:103]
	v_mfma_f32_16x16x32_bf16 v[96:99], v[180:183], v[196:199], v[96:99]
	v_mfma_f32_16x16x32_bf16 v[84:87], v[170:173], v[204:207], v[84:87]
	v_mfma_f32_16x16x32_bf16 v[80:83], v[180:183], v[204:207], v[80:83]
	v_mfma_f32_16x16x32_bf16 v[68:71], v[170:173], v[212:215], v[68:71]
	v_mfma_f32_16x16x32_bf16 v[64:67], v[180:183], v[212:215], v[64:67]
	s_setprio 0
	s_barrier
;     __device__ __forceinline__ void operator()(const f32x4 (&acc)[2][2][4][2], const Unit& u, int wr, int wc, int fr, int fq) const {
;         const int row0 = u.pm * BM + wr * 64 + fr, col0 = u.pn * 128 + wc * 32 + 8 * fq;
; #pragma unroll
;         for (int ai = 0; ai < 2; ++ai)
; #pragma unroll
;             for (int m = 0; m < 4; ++m) { bf16_t* rowp = out + (size_t)(row0 + ai * HALF + m * 16) * 2816 + col0;
; template <class Epi, class Sched, bool ALIGN_EPI = false, bool SP2 = false>
; __device__ __forceinline__ void gemm_phase(PG8_LAS unsigned char* lds, const Gemm g, const Sched& S, const Epi& E) {
;     ...
;             PG8_LDA(At, 1, 1); PG8_STAGE(PG8_SB(1, 0), b3, voffB); PG8_STAGE(PG8_SB(1, 1), b3 + hstepB, voffB); PG8_STAGE(PG8_SA(1, 0), a3, voffA);
;             PG8_WAIT_V(8); PG8_WAIT_L(0); PG8_BAR; PG8_MMA(1, 0, At, B0); PG8_MMA(1, 1, At, B1); PG8_BAR; PG8_SCHED;
;             } else {
;             PG8_LDB(B0, 0, 0); PG8_SCHED; PG8_LDA(At, 0, 0); PG8_STAGE(PG8_SA(1, 1), a1 + hstepA, voffA);
;             PG8_WAIT_L(8); PG8_BAR; PG8_WAIT_L(0); PG8_MMA(0, 0, At, B0); PG8_BAR; PG8_SCHED;
;             PG8_LDB(B1, 0, 1); PG8_STAGE(PG8_SB(0, 0), b2, voffB);
;             PG8_BAR; PG8_WAIT_L(0); PG8_MMA(0, 1, At, B1); PG8_BAR;
;             PG8_LDA(At, 0, 1); PG8_STAGE(PG8_SA(0, 0), a2, voffA);
;             PG8_BAR; PG8_WAIT_L(0); PG8_MMA(1, 0, At, B0); PG8_BAR; PG8_SCHED;
;             PG8_STAGE(PG8_SB(0, 1), b2 + hstepB, voffB);
;             PG8_WAIT_V(6); PG8_BAR; PG8_MMA(1, 1, At, B1); PG8_BAR;
;             PG8_LDB(B0, 1, 0); PG8_SCHED; PG8_LDA(At, 1, 0); PG8_STAGE(PG8_SA(0, 1), a2 + hstepA, voffA);
;             PG8_WAIT_L(8); PG8_BAR; PG8_WAIT_L(0); PG8_MMA(0, 0, At, B0); PG8_BAR; PG8_SCHED;
;             PG8_LDB(B1, 1, 1); PG8_STAGE(PG8_SB(1, 0), b3, voffB);
;             PG8_BAR; PG8_WAIT_L(0); PG8_MMA(0, 1, At, B1); PG8_BAR;
;             PG8_LDA(At, 1, 1); PG8_STAGE(PG8_SA(1, 0), a3, voffA);
;             PG8_BAR; PG8_WAIT_L(0); PG8_MMA(1, 0, At, B0); PG8_BAR; PG8_SCHED;
;             PG8_STAGE(PG8_SB(1, 1), b3 + hstepB, voffB);
;             PG8_WAIT_V(6); PG8_BAR; PG8_MMA(1, 1, At, B1); PG8_BAR;
;             }
;         }
;         if constexpr (ALIGN_EPI) { if (wr == 0) PG8_BAR; }
;         if constexpr (!Epi::AFTER_DRAIN) { E(acc, cur, wr, wc, fr, fq); S.done(cur); }
;         if (!has_next) break;
	s_add_i32 s33, s33, s22
	v_lshl_add_u64 v[216:217], v[216:217], 0, s[6:7]
	s_mov_b32 m0, s33
	ds_read_b128 v[184:187], v153 offset:49152
	ds_read_b128 v[188:191], v153 offset:50176
	ds_read_b128 v[192:195], v153 offset:51200
	ds_read_b128 v[196:199], v153 offset:52224
	ds_read_b128 v[200:203], v153 offset:53248
	ds_read_b128 v[204:207], v153 offset:54272
	ds_read_b128 v[208:211], v153 offset:55296
	ds_read_b128 v[212:215], v153 offset:56320
	global_load_lds_dwordx4 v[216:217], off
	s_add_i32 m0, s33, 0x2000
	s_add_u32 s40, s40, 0x40080
	v_lshl_add_u64 v[216:217], v[218:219], 0, s[6:7]
	s_addc_u32 s41, s41, 0
	s_add_i32 s33, s57, s22
	global_load_lds_dwordx4 v[216:217], off
	v_lshl_add_u64 v[216:217], s[40:41], 0, v[132:133]
	s_mov_b32 m0, s33
	s_nop 0
	global_load_lds_dwordx4 v[216:217], off
	v_lshl_add_u64 v[216:217], s[40:41], 0, v[128:129]
	s_add_i32 m0, s33, 0x2000
	s_nop 0
	global_load_lds_dwordx4 v[216:217], off
	v_lshl_add_u64 v[216:217], v[220:221], 0, s[6:7]
	s_mov_b32 m0, s44
	s_nop 0
	global_load_lds_dwordx4 v[216:217], off
	v_lshl_add_u64 v[216:217], v[222:223], 0, s[6:7]
	s_mov_b32 m0, s45
	s_nop 0
	global_load_lds_dwordx4 v[216:217], off
	s_waitcnt vmcnt(8)
	s_waitcnt lgkmcnt(0)
	s_barrier
	s_setprio 1
	s_waitcnt lgkmcnt(0)
	v_mfma_f32_16x16x32_bf16 v[60:63], v[144:147], v[184:187], v[60:63]
	v_mfma_f32_16x16x32_bf16 v[56:59], v[158:161], v[184:187], v[56:59]
	v_mfma_f32_16x16x32_bf16 v[44:47], v[144:147], v[192:195], v[44:47]
	v_mfma_f32_16x16x32_bf16 v[40:43], v[158:161], v[192:195], v[40:43]
	v_mfma_f32_16x16x32_bf16 v[28:31], v[144:147], v[200:203], v[28:31]
	v_mfma_f32_16x16x32_bf16 v[24:27], v[158:161], v[200:203], v[24:27]
	v_mfma_f32_16x16x32_bf16 v[12:15], v[144:147], v[208:211], v[12:15]
	v_mfma_f32_16x16x32_bf16 v[8:11], v[158:161], v[208:211], v[8:11]
	v_mfma_f32_16x16x32_bf16 v[60:63], v[154:157], v[188:191], v[60:63]
	v_mfma_f32_16x16x32_bf16 v[56:59], v[162:165], v[188:191], v[56:59]
	v_mfma_f32_16x16x32_bf16 v[44:47], v[154:157], v[196:199], v[44:47]
	v_mfma_f32_16x16x32_bf16 v[40:43], v[162:165], v[196:199], v[40:43]
	v_mfma_f32_16x16x32_bf16 v[28:31], v[154:157], v[204:207], v[28:31]
	v_mfma_f32_16x16x32_bf16 v[24:27], v[162:165], v[204:207], v[24:27]
	v_mfma_f32_16x16x32_bf16 v[12:15], v[154:157], v[212:215], v[12:15]
	v_mfma_f32_16x16x32_bf16 v[8:11], v[162:165], v[212:215], v[8:11]
	s_setprio 0
	s_setprio 1
	v_mfma_f32_16x16x32_bf16 v[52:55], v[166:169], v[184:187], v[52:55]
	v_mfma_f32_16x16x32_bf16 v[48:51], v[176:179], v[184:187], v[48:51]
	v_mfma_f32_16x16x32_bf16 v[36:39], v[166:169], v[192:195], v[36:39]
	v_mfma_f32_16x16x32_bf16 v[32:35], v[176:179], v[192:195], v[32:35]
	v_mfma_f32_16x16x32_bf16 v[20:23], v[166:169], v[200:203], v[20:23]
	v_mfma_f32_16x16x32_bf16 v[16:19], v[176:179], v[200:203], v[16:19]
	v_mfma_f32_16x16x32_bf16 v[4:7], v[166:169], v[208:211], v[4:7]
	v_mfma_f32_16x16x32_bf16 v[0:3], v[176:179], v[208:211], v[0:3]
	v_mfma_f32_16x16x32_bf16 v[52:55], v[170:173], v[188:191], v[52:55]
	v_mfma_f32_16x16x32_bf16 v[48:51], v[180:183], v[188:191], v[48:51]
	v_mfma_f32_16x16x32_bf16 v[36:39], v[170:173], v[196:199], v[36:39]
	v_mfma_f32_16x16x32_bf16 v[32:35], v[180:183], v[196:199], v[32:35]
	v_mfma_f32_16x16x32_bf16 v[20:23], v[170:173], v[204:207], v[20:23]
	v_mfma_f32_16x16x32_bf16 v[16:19], v[180:183], v[204:207], v[16:19]
	v_mfma_f32_16x16x32_bf16 v[4:7], v[170:173], v[212:215], v[4:7]
	v_mfma_f32_16x16x32_bf16 v[0:3], v[180:183], v[212:215], v[0:3]
	s_setprio 0
	s_barrier
	s_add_i32 s56, s56, 2
	s_add_u32 s38, s38, 0x100
	s_addc_u32 s39, s39, 0
	s_add_u32 s54, s54, 0x100
	s_addc_u32 s55, s55, 0
	s_cmp_gt_u32 s56, 13
	s_cbranch_scc0 .LBB0_605
	s_and_b64 vcc, exec, s[2:3]
	s_cbranch_vccz .Lold_epi_p7
	s_add_u32 s100, s52, 0x40080
	s_addc_u32 s101, s13, 0
	v_lshl_add_u64 v[216:217], s[100:101], 0, v[136:137]
	s_add_i32 m0, s29, 0xc000
	v_lshl_add_u64 v[218:219], s[100:101], 0, v[138:139]
	global_load_lds_dwordx4 v[216:217], off
	s_add_i32 m0, s29, 0xe000
	s_nop 0
	global_load_lds_dwordx4 v[218:219], off
	v_lshl_add_u32 v234, s36, 8, v148
	v_mul_u32_u24_e32 v234, 0x1600, v234
	v_lshl_or_b32 v235, s51, 7, v150
	v_lshl_add_u32 v234, v235, 1, v234
	s_branch .LBB0_600
.Lold_epi_p7:
	s_and_b64 vcc, exec, s[8:9]
	s_cbranch_vccz .LBB0_608
	s_barrier

; __device__ __forceinline__ unsigned cvt_pk_bf16(float lo, float hi) { unsigned r; asm volatile("v_cvt_pk_bf16_f32 %0, %1, %2" : "=v"(r) : "v"(lo), "v"(hi)); return r; }
; __device__ __forceinline__ float sigm(float x) { return __builtin_amdgcn_rcpf(1.0f + __builtin_amdgcn_exp2f(-1.4426950408889634f * x)); }
; #define PG8_STAGE(bufoff, gbase, voff) do { _Pragma("unroll") for (int _i = 0; _i < 2; ++_i) \
;         __builtin_amdgcn_global_load_lds((const unsigned*)((const char*)(gbase) + (voff)[_i]), (PG8_LAS unsigned*)(lds + (bufoff) + ldsw + _i * 8192), 16, 0, 0); } while (0)
; #define PG8_LDA(dst, b, h) do { _Pragma("unroll") for (int m = 0; m < 4; ++m) _Pragma("unroll") for (int k = 0; k < 2; ++k) dst[m][k] = *(const PG8_LAS bf16x8*)(lds + PG8_SA(b, h) + aoff + m * 2048 + k * 1024); } while (0)
; #define PG8_WAIT_V(n) asm volatile("s_waitcnt vmcnt(" #n ")" ::: "memory")
; #define PG8_BAR __builtin_amdgcn_s_barrier()
;     __device__ __forceinline__ void operator()(const f32x4 (&acc)[2][2][4][2], const Unit& u, int wr, int wc, int fr, int fq) const {
;         const int row0 = u.pm * BM + wr * 64 + fr, col0 = u.pn * 128 + wc * 32 + 8 * fq;
; #pragma unroll
;         for (int ai = 0; ai < 2; ++ai)
; #pragma unroll
;             for (int m = 0; m < 4; ++m) { bf16_t* rowp = out + (size_t)(row0 + ai * HALF + m * 16) * 2816 + col0;
;                 const f32x4 g0 = acc[ai][0][m][0], g1 = acc[ai][0][m][1], u0 = acc[ai][1][m][0], u1 = acc[ai][1][m][1];
;                 u32x4 w;
;                 w.x = cvt_pk_bf16(g0[0] * sigm(g0[0]) * u0[0], g0[1] * sigm(g0[1]) * u0[1]);
;                 w.y = cvt_pk_bf16(g0[2] * sigm(g0[2]) * u0[2], g0[3] * sigm(g0[3]) * u0[3]);
;                 w.z = cvt_pk_bf16(g1[0] * sigm(g1[0]) * u1[0], g1[1] * sigm(g1[1]) * u1[1]);
;                 w.w = cvt_pk_bf16(g1[2] * sigm(g1[2]) * u1[2], g1[3] * sigm(g1[3]) * u1[3]);
;                 __builtin_nontemporal_store(w, (u32x4*)rowp); }
; template <class Epi, class Sched, bool ALIGN_EPI = false, bool SP2 = false>
; __device__ __forceinline__ void gemm_phase(PG8_LAS unsigned char* lds, const Gemm g, const Sched& S, const Epi& E) {
;     ...
;             PG8_LDB(B0, 0, 0); PG8_LDB(B1, 0, 1); PG8_SCHED; PG8_LDA(At, 0, 0); PG8_STAGE(PG8_SA(1, 1), a1 + hstepA, voffA);
;             PG8_WAIT_V(8); PG8_WAIT_L(0); PG8_BAR; PG8_MMA(0, 0, At, B0); PG8_MMA(0, 1, At, B1); PG8_BAR; PG8_SCHED;
.Lpeel_p7:
	ds_read_b128 v[144:147], v151
	ds_read_b128 v[154:157], v151 offset:1024
	ds_read_b128 v[158:161], v151 offset:2048
	ds_read_b128 v[162:165], v151 offset:3072
	ds_read_b128 v[166:169], v152
	ds_read_b128 v[170:173], v152 offset:1024
	ds_read_b128 v[176:179], v152 offset:2048
	ds_read_b128 v[180:183], v152 offset:3072
	s_add_u32 s33, s38, 0xfffc0080
	s_addc_u32 s40, s39, -1
	s_cmp_eq_u32 s56, 12
	s_cselect_b32 s43, s13, s40
	s_cselect_b32 s42, s52, s33
	s_cselect_b32 s41, s11, s55
	s_cselect_b32 s40, s53, s54
	ds_read_b128 v[184:187], v153
	ds_read_b128 v[188:191], v153 offset:1024
	ds_read_b128 v[192:195], v153 offset:2048
	ds_read_b128 v[196:199], v153 offset:3072
	ds_read_b128 v[200:203], v153 offset:4096
	ds_read_b128 v[204:207], v153 offset:5120
	ds_read_b128 v[208:211], v153 offset:6144
	ds_read_b128 v[212:215], v153 offset:7168
	v_mul_f32_e32 v226, 0xbfb8aa3b, v124
	v_mul_f32_e32 v227, 0xbfb8aa3b, v125
	v_mul_f32_e32 v228, 0xbfb8aa3b, v126
	v_mul_f32_e32 v229, 0xbfb8aa3b, v127
	v_exp_f32_e32 v226, v226
	v_exp_f32_e32 v227, v227
	v_exp_f32_e32 v228, v228
	v_exp_f32_e32 v229, v229
	v_add_f32_e32 v226, 1.0, v226
	v_add_f32_e32 v227, 1.0, v227
	v_add_f32_e32 v228, 1.0, v228
	v_add_f32_e32 v229, 1.0, v229
	v_rcp_f32_e32 v226, v226
	v_rcp_f32_e32 v227, v227
	v_rcp_f32_e32 v228, v228
	v_rcp_f32_e32 v229, v229
	v_mul_f32_e32 v226, v124, v226
	v_mul_f32_e32 v227, v125, v227
	v_mul_f32_e32 v228, v126, v228
	v_mul_f32_e32 v229, v127, v229
	v_mul_f32_e32 v116, v226, v116
	v_mul_f32_e32 v117, v227, v117
	v_mul_f32_e32 v118, v228, v118
	v_mul_f32_e32 v119, v229, v119
	v_mul_f32_e32 v226, 0xbfb8aa3b, v120
	v_mul_f32_e32 v227, 0xbfb8aa3b, v121
	v_mul_f32_e32 v228, 0xbfb8aa3b, v122
	v_mul_f32_e32 v229, 0xbfb8aa3b, v123
	v_exp_f32_e32 v226, v226
	v_exp_f32_e32 v227, v227
	v_exp_f32_e32 v228, v228
	v_exp_f32_e32 v229, v229
	v_add_f32_e32 v226, 1.0, v226
	v_add_f32_e32 v227, 1.0, v227
	v_add_f32_e32 v228, 1.0, v228
	v_add_f32_e32 v229, 1.0, v229
	v_rcp_f32_e32 v226, v226
	v_rcp_f32_e32 v227, v227
	v_rcp_f32_e32 v228, v228
	v_rcp_f32_e32 v229, v229
	v_mul_f32_e32 v226, v120, v226
	v_mul_f32_e32 v227, v121, v227
	v_mul_f32_e32 v228, v122, v228
	v_mul_f32_e32 v229, v123, v229
	v_mul_f32_e32 v112, v226, v112
	v_mul_f32_e32 v113, v227, v113
	v_mul_f32_e32 v114, v228, v114
	v_mul_f32_e32 v115, v229, v115
	v_cvt_pk_bf16_f32 v116, v116, v117
	v_cvt_pk_bf16_f32 v117, v118, v119
	v_cvt_pk_bf16_f32 v118, v112, v113
	v_cvt_pk_bf16_f32 v119, v114, v115
	s_nop 0
	global_store_dwordx4 v234, v[116:119], s[18:19] nt
	v_mul_f32_e32 v226, 0xbfb8aa3b, v108
	v_mul_f32_e32 v227, 0xbfb8aa3b, v109
	v_mul_f32_e32 v228, 0xbfb8aa3b, v110
	v_mul_f32_e32 v229, 0xbfb8aa3b, v111
	v_exp_f32_e32 v226, v226
	v_exp_f32_e32 v227, v227
	v_exp_f32_e32 v228, v228
	v_exp_f32_e32 v229, v229
	v_add_f32_e32 v226, 1.0, v226
	v_add_f32_e32 v227, 1.0, v227
	v_add_f32_e32 v228, 1.0, v228
	v_add_f32_e32 v229, 1.0, v229
	v_rcp_f32_e32 v226, v226
	v_rcp_f32_e32 v227, v227
	v_rcp_f32_e32 v228, v228
	v_rcp_f32_e32 v229, v229
	v_mul_f32_e32 v226, v108, v226
	v_mul_f32_e32 v227, v109, v227
	v_mul_f32_e32 v228, v110, v228
	v_mul_f32_e32 v229, v111, v229
	v_mul_f32_e32 v100, v226, v100
	v_mul_f32_e32 v101, v227, v101
	v_mul_f32_e32 v102, v228, v102
	v_mul_f32_e32 v103, v229, v103
	v_mul_f32_e32 v226, 0xbfb8aa3b, v104
	v_mul_f32_e32 v227, 0xbfb8aa3b, v105
	v_mul_f32_e32 v228, 0xbfb8aa3b, v106
	v_mul_f32_e32 v229, 0xbfb8aa3b, v107
	v_exp_f32_e32 v226, v226
	v_exp_f32_e32 v227, v227
	v_exp_f32_e32 v228, v228
	v_exp_f32_e32 v229, v229
	v_add_f32_e32 v226, 1.0, v226
	v_add_f32_e32 v227, 1.0, v227
	v_add_f32_e32 v228, 1.0, v228
	v_add_f32_e32 v229, 1.0, v229
	v_rcp_f32_e32 v226, v226
	v_rcp_f32_e32 v227, v227
	v_rcp_f32_e32 v228, v228
	v_rcp_f32_e32 v229, v229
	v_mul_f32_e32 v226, v104, v226
	v_mul_f32_e32 v227, v105, v227
	v_mul_f32_e32 v228, v106, v228
	v_mul_f32_e32 v229, v107, v229
	v_mul_f32_e32 v96, v226, v96
	v_mul_f32_e32 v97, v227, v97
	v_mul_f32_e32 v98, v228, v98
	v_mul_f32_e32 v99, v229, v99
	v_cvt_pk_bf16_f32 v100, v100, v101
	v_cvt_pk_bf16_f32 v101, v102, v103
	v_cvt_pk_bf16_f32 v102, v96, v97
	v_cvt_pk_bf16_f32 v103, v98, v99
	v_add_u32_e32 v235, 0x16000, v234
	s_nop 0
	global_store_dwordx4 v235, v[100:103], s[18:19] nt
	v_mul_f32_e32 v226, 0xbfb8aa3b, v92
	v_mul_f32_e32 v227, 0xbfb8aa3b, v93
	v_mul_f32_e32 v228, 0xbfb8aa3b, v94
	v_mul_f32_e32 v229, 0xbfb8aa3b, v95
	v_exp_f32_e32 v226, v226
	v_exp_f32_e32 v227, v227
	v_exp_f32_e32 v228, v228
	v_exp_f32_e32 v229, v229
	v_add_f32_e32 v226, 1.0, v226
	v_add_f32_e32 v227, 1.0, v227
	v_add_f32_e32 v228, 1.0, v228
	v_add_f32_e32 v229, 1.0, v229
	v_rcp_f32_e32 v226, v226
	v_rcp_f32_e32 v227, v227
	v_rcp_f32_e32 v228, v228
	v_rcp_f32_e32 v229, v229
	v_mul_f32_e32 v226, v92, v226
	v_mul_f32_e32 v227, v93, v227
	v_mul_f32_e32 v228, v94, v228
	v_mul_f32_e32 v229, v95, v229
	v_mul_f32_e32 v84, v226, v84
	v_mul_f32_e32 v85, v227, v85
	v_mul_f32_e32 v86, v228, v86
	v_mul_f32_e32 v87, v229, v87
	v_mul_f32_e32 v226, 0xbfb8aa3b, v88
	v_mul_f32_e32 v227, 0xbfb8aa3b, v89
	v_mul_f32_e32 v228, 0xbfb8aa3b, v90
	v_mul_f32_e32 v229, 0xbfb8aa3b, v91
	v_exp_f32_e32 v226, v226
	v_exp_f32_e32 v227, v227
	v_exp_f32_e32 v228, v228
	v_exp_f32_e32 v229, v229
	v_add_f32_e32 v226, 1.0, v226
	v_add_f32_e32 v227, 1.0, v227
	v_add_f32_e32 v228, 1.0, v228
	v_add_f32_e32 v229, 1.0, v229
	v_rcp_f32_e32 v226, v226
	v_rcp_f32_e32 v227, v227
	v_rcp_f32_e32 v228, v228
	v_rcp_f32_e32 v229, v229
	v_mul_f32_e32 v226, v88, v226
	v_mul_f32_e32 v227, v89, v227
	v_mul_f32_e32 v228, v90, v228
	v_mul_f32_e32 v229, v91, v229
	v_mul_f32_e32 v80, v226, v80
	v_mul_f32_e32 v81, v227, v81
; __device__ __forceinline__ unsigned cvt_pk_bf16(float lo, float hi) { unsigned r; asm volatile("v_cvt_pk_bf16_f32 %0, %1, %2" : "=v"(r) : "v"(lo), "v"(hi)); return r; }
; __device__ __forceinline__ float sigm(float x) { return __builtin_amdgcn_rcpf(1.0f + __builtin_amdgcn_exp2f(-1.4426950408889634f * x)); }
; #define PG8_STAGE(bufoff, gbase, voff) do { _Pragma("unroll") for (int _i = 0; _i < 2; ++_i) \
;         __builtin_amdgcn_global_load_lds((const unsigned*)((const char*)(gbase) + (voff)[_i]), (PG8_LAS unsigned*)(lds + (bufoff) + ldsw + _i * 8192), 16, 0, 0); } while (0)
; #define PG8_LDA(dst, b, h) do { _Pragma("unroll") for (int m = 0; m < 4; ++m) _Pragma("unroll") for (int k = 0; k < 2; ++k) dst[m][k] = *(const PG8_LAS bf16x8*)(lds + PG8_SA(b, h) + aoff + m * 2048 + k * 1024); } while (0)
; #define PG8_WAIT_V(n) asm volatile("s_waitcnt vmcnt(" #n ")" ::: "memory")
;     __device__ __forceinline__ void operator()(const f32x4 (&acc)[2][2][4][2], const Unit& u, int wr, int wc, int fr, int fq) const {
;         const int row0 = u.pm * BM + wr * 64 + fr, col0 = u.pn * 128 + wc * 32 + 8 * fq;
; #pragma unroll
;         for (int ai = 0; ai < 2; ++ai)
; #pragma unroll
;             for (int m = 0; m < 4; ++m) { bf16_t* rowp = out + (size_t)(row0 + ai * HALF + m * 16) * 2816 + col0;
;                 const f32x4 g0 = acc[ai][0][m][0], g1 = acc[ai][0][m][1], u0 = acc[ai][1][m][0], u1 = acc[ai][1][m][1];
;                 u32x4 w;
;                 w.x = cvt_pk_bf16(g0[0] * sigm(g0[0]) * u0[0], g0[1] * sigm(g0[1]) * u0[1]);
;                 w.y = cvt_pk_bf16(g0[2] * sigm(g0[2]) * u0[2], g0[3] * sigm(g0[3]) * u0[3]);
;                 w.z = cvt_pk_bf16(g1[0] * sigm(g1[0]) * u1[0], g1[1] * sigm(g1[1]) * u1[1]);
;                 w.w = cvt_pk_bf16(g1[2] * sigm(g1[2]) * u1[2], g1[3] * sigm(g1[3]) * u1[3]);
;                 __builtin_nontemporal_store(w, (u32x4*)rowp); }
; template <class Epi, class Sched, bool ALIGN_EPI = false, bool SP2 = false>
; __device__ __forceinline__ void gemm_phase(PG8_LAS unsigned char* lds, const Gemm g, const Sched& S, const Epi& E) {
;     ...
;             PG8_WAIT_V(8); PG8_WAIT_L(0); PG8_BAR; PG8_MMA(0, 0, At, B0); PG8_MMA(0, 1, At, B1); PG8_BAR; PG8_SCHED;
;             PG8_LDA(At, 0, 1); PG8_STAGE(PG8_SB(0, 0), b2, voffB); PG8_STAGE(PG8_SB(0, 1), b2 + hstepB, voffB); PG8_STAGE(PG8_SA(0, 0), a2, voffA);
	v_mul_f32_e32 v82, v228, v82
	v_mul_f32_e32 v83, v229, v83
	v_cvt_pk_bf16_f32 v84, v84, v85
	v_cvt_pk_bf16_f32 v85, v86, v87
	v_cvt_pk_bf16_f32 v86, v80, v81
	v_cvt_pk_bf16_f32 v87, v82, v83
	v_add_u32_e32 v235, 0x2c000, v234
	s_nop 0
	global_store_dwordx4 v235, v[84:87], s[18:19] nt
	v_mul_f32_e32 v226, 0xbfb8aa3b, v76
	v_mul_f32_e32 v227, 0xbfb8aa3b, v77
	v_mul_f32_e32 v228, 0xbfb8aa3b, v78
	v_mul_f32_e32 v229, 0xbfb8aa3b, v79
	v_exp_f32_e32 v226, v226
	v_exp_f32_e32 v227, v227
	v_exp_f32_e32 v228, v228
	v_exp_f32_e32 v229, v229
	v_add_f32_e32 v226, 1.0, v226
	v_add_f32_e32 v227, 1.0, v227
	v_add_f32_e32 v228, 1.0, v228
	v_add_f32_e32 v229, 1.0, v229
	v_rcp_f32_e32 v226, v226
	v_rcp_f32_e32 v227, v227
	v_rcp_f32_e32 v228, v228
	v_rcp_f32_e32 v229, v229
	v_mul_f32_e32 v226, v76, v226
	v_mul_f32_e32 v227, v77, v227
	v_mul_f32_e32 v228, v78, v228
	v_mul_f32_e32 v229, v79, v229
	v_mul_f32_e32 v68, v226, v68
	v_mul_f32_e32 v69, v227, v69
	v_mul_f32_e32 v70, v228, v70
	v_mul_f32_e32 v71, v229, v71
	v_mul_f32_e32 v226, 0xbfb8aa3b, v72
	v_mul_f32_e32 v227, 0xbfb8aa3b, v73
	v_mul_f32_e32 v228, 0xbfb8aa3b, v74
	v_mul_f32_e32 v229, 0xbfb8aa3b, v75
	v_exp_f32_e32 v226, v226
	v_exp_f32_e32 v227, v227
	v_exp_f32_e32 v228, v228
	v_exp_f32_e32 v229, v229
	v_add_f32_e32 v226, 1.0, v226
	v_add_f32_e32 v227, 1.0, v227
	v_add_f32_e32 v228, 1.0, v228
	v_add_f32_e32 v229, 1.0, v229
	v_rcp_f32_e32 v226, v226
	v_rcp_f32_e32 v227, v227
	v_rcp_f32_e32 v228, v228
	v_rcp_f32_e32 v229, v229
	v_mul_f32_e32 v226, v72, v226
	v_mul_f32_e32 v227, v73, v227
	v_mul_f32_e32 v228, v74, v228
	v_mul_f32_e32 v229, v75, v229
	v_mul_f32_e32 v64, v226, v64
	v_mul_f32_e32 v65, v227, v65
	v_mul_f32_e32 v66, v228, v66
	v_mul_f32_e32 v67, v229, v67
	v_cvt_pk_bf16_f32 v68, v68, v69
	v_cvt_pk_bf16_f32 v69, v70, v71
	v_cvt_pk_bf16_f32 v70, v64, v65
	v_cvt_pk_bf16_f32 v71, v66, v67
	v_add_u32_e32 v235, 0x42000, v234
	s_nop 0
	global_store_dwordx4 v235, v[68:71], s[18:19] nt
	s_waitcnt vmcnt(12)
	s_waitcnt lgkmcnt(0)
	s_barrier
	s_setprio 1
	s_waitcnt lgkmcnt(0)
	v_mfma_f32_16x16x32_bf16 v[124:127], v[144:147], v[184:187], 0
	v_mfma_f32_16x16x32_bf16 v[120:123], v[158:161], v[184:187], 0
	v_mfma_f32_16x16x32_bf16 v[108:111], v[144:147], v[192:195], 0
	v_mfma_f32_16x16x32_bf16 v[104:107], v[158:161], v[192:195], 0
	v_mfma_f32_16x16x32_bf16 v[92:95], v[144:147], v[200:203], 0
	v_mfma_f32_16x16x32_bf16 v[88:91], v[158:161], v[200:203], 0
	v_mfma_f32_16x16x32_bf16 v[76:79], v[144:147], v[208:211], 0
	v_mfma_f32_16x16x32_bf16 v[72:75], v[158:161], v[208:211], 0
	v_mfma_f32_16x16x32_bf16 v[124:127], v[154:157], v[188:191], v[124:127]
	v_mfma_f32_16x16x32_bf16 v[120:123], v[162:165], v[188:191], v[120:123]
	v_mfma_f32_16x16x32_bf16 v[108:111], v[154:157], v[196:199], v[108:111]
	v_mfma_f32_16x16x32_bf16 v[104:107], v[162:165], v[196:199], v[104:107]
	v_mfma_f32_16x16x32_bf16 v[92:95], v[154:157], v[204:207], v[92:95]
	v_mfma_f32_16x16x32_bf16 v[88:91], v[162:165], v[204:207], v[88:91]
	v_mfma_f32_16x16x32_bf16 v[76:79], v[154:157], v[212:215], v[76:79]
	v_mfma_f32_16x16x32_bf16 v[72:75], v[162:165], v[212:215], v[72:75]
	s_setprio 0
	s_setprio 1
	v_mfma_f32_16x16x32_bf16 v[116:119], v[166:169], v[184:187], 0
	v_mfma_f32_16x16x32_bf16 v[112:115], v[176:179], v[184:187], 0
	v_mfma_f32_16x16x32_bf16 v[100:103], v[166:169], v[192:195], 0
	v_mfma_f32_16x16x32_bf16 v[96:99], v[176:179], v[192:195], 0
	v_mfma_f32_16x16x32_bf16 v[84:87], v[166:169], v[200:203], 0
	v_mfma_f32_16x16x32_bf16 v[80:83], v[176:179], v[200:203], 0
	v_mfma_f32_16x16x32_bf16 v[68:71], v[166:169], v[208:211], 0
	v_mfma_f32_16x16x32_bf16 v[64:67], v[176:179], v[208:211], 0
	v_mfma_f32_16x16x32_bf16 v[116:119], v[170:173], v[188:191], v[116:119]
	v_mfma_f32_16x16x32_bf16 v[112:115], v[180:183], v[188:191], v[112:115]
	v_mfma_f32_16x16x32_bf16 v[100:103], v[170:173], v[196:199], v[100:103]
	v_mfma_f32_16x16x32_bf16 v[96:99], v[180:183], v[196:199], v[96:99]
	v_mfma_f32_16x16x32_bf16 v[84:87], v[170:173], v[204:207], v[84:87]
	v_mfma_f32_16x16x32_bf16 v[80:83], v[180:183], v[204:207], v[80:83]
	v_mfma_f32_16x16x32_bf16 v[68:71], v[170:173], v[212:215], v[68:71]
	v_mfma_f32_16x16x32_bf16 v[64:67], v[180:183], v[212:215], v[64:67]
	s_setprio 0
	s_barrier
; __device__ __forceinline__ unsigned cvt_pk_bf16(float lo, float hi) { unsigned r; asm volatile("v_cvt_pk_bf16_f32 %0, %1, %2" : "=v"(r) : "v"(lo), "v"(hi)); return r; }
; __device__ __forceinline__ float sigm(float x) { return __builtin_amdgcn_rcpf(1.0f + __builtin_amdgcn_exp2f(-1.4426950408889634f * x)); }
; #define PG8_STAGE(bufoff, gbase, voff) do { _Pragma("unroll") for (int _i = 0; _i < 2; ++_i) \
;         __builtin_amdgcn_global_load_lds((const unsigned*)((const char*)(gbase) + (voff)[_i]), (PG8_LAS unsigned*)(lds + (bufoff) + ldsw + _i * 8192), 16, 0, 0); } while (0)
; #define PG8_LDA(dst, b, h) do { _Pragma("unroll") for (int m = 0; m < 4; ++m) _Pragma("unroll") for (int k = 0; k < 2; ++k) dst[m][k] = *(const PG8_LAS bf16x8*)(lds + PG8_SA(b, h) + aoff + m * 2048 + k * 1024); } while (0)
; #define PG8_WAIT_V(n) asm volatile("s_waitcnt vmcnt(" #n ")" ::: "memory")
;     __device__ __forceinline__ void operator()(const f32x4 (&acc)[2][2][4][2], const Unit& u, int wr, int wc, int fr, int fq) const {
;         const int row0 = u.pm * BM + wr * 64 + fr, col0 = u.pn * 128 + wc * 32 + 8 * fq;
; #pragma unroll
;         for (int ai = 0; ai < 2; ++ai)
; #pragma unroll
;             for (int m = 0; m < 4; ++m) { bf16_t* rowp = out + (size_t)(row0 + ai * HALF + m * 16) * 2816 + col0;
;                 const f32x4 g0 = acc[ai][0][m][0], g1 = acc[ai][0][m][1], u0 = acc[ai][1][m][0], u1 = acc[ai][1][m][1];
;                 u32x4 w;
;                 w.x = cvt_pk_bf16(g0[0] * sigm(g0[0]) * u0[0], g0[1] * sigm(g0[1]) * u0[1]);
;                 w.y = cvt_pk_bf16(g0[2] * sigm(g0[2]) * u0[2], g0[3] * sigm(g0[3]) * u0[3]);
;                 w.z = cvt_pk_bf16(g1[0] * sigm(g1[0]) * u1[0], g1[1] * sigm(g1[1]) * u1[1]);
;                 w.w = cvt_pk_bf16(g1[2] * sigm(g1[2]) * u1[2], g1[3] * sigm(g1[3]) * u1[3]);
;                 __builtin_nontemporal_store(w, (u32x4*)rowp); }
; template <class Epi, class Sched, bool ALIGN_EPI = false, bool SP2 = false>
; __device__ __forceinline__ void gemm_phase(PG8_LAS unsigned char* lds, const Gemm g, const Sched& S, const Epi& E) {
;     ...
;             PG8_LDA(At, 0, 1); PG8_STAGE(PG8_SB(0, 0), b2, voffB); PG8_STAGE(PG8_SB(0, 1), b2 + hstepB, voffB); PG8_STAGE(PG8_SA(0, 0), a2, voffA);
;             PG8_WAIT_V(8); PG8_WAIT_L(0); PG8_BAR; PG8_MMA(1, 0, At, B0); PG8_MMA(1, 1, At, B1); PG8_BAR; PG8_SCHED;
	s_add_i32 s33, s48, s22
	v_lshl_add_u64 v[216:217], s[40:41], 0, v[132:133]
	s_mov_b32 m0, s33
	ds_read_b128 v[184:187], v153 offset:16384
	ds_read_b128 v[188:191], v153 offset:17408
	ds_read_b128 v[192:195], v153 offset:18432
	ds_read_b128 v[196:199], v153 offset:19456
	ds_read_b128 v[200:203], v153 offset:20480
	ds_read_b128 v[204:207], v153 offset:21504
	ds_read_b128 v[208:211], v153 offset:22528
	ds_read_b128 v[212:215], v153 offset:23552
	global_load_lds_dwordx4 v[216:217], off
	s_add_i32 m0, s33, 0x2000
	s_add_u32 s58, s40, 0x40000
	v_lshl_add_u64 v[218:219], s[40:41], 0, v[128:129]
	s_addc_u32 s59, s41, 0
	s_add_i32 s33, s49, s22
	global_load_lds_dwordx4 v[218:219], off
	v_lshl_add_u64 v[220:221], s[58:59], 0, v[132:133]
	s_mov_b32 m0, s33
	v_lshl_add_u64 v[222:223], s[42:43], 0, v[130:131]
	global_load_lds_dwordx4 v[220:221], off
	v_lshl_add_u64 v[220:221], s[58:59], 0, v[128:129]
	s_add_i32 m0, s33, 0x2000
	s_nop 0
	global_load_lds_dwordx4 v[220:221], off
	v_lshl_add_u64 v[220:221], s[42:43], 0, v[134:135]
	s_mov_b32 m0, s29
	s_nop 0
	global_load_lds_dwordx4 v[220:221], off
	s_mov_b32 m0, s30
	s_nop 0
	global_load_lds_dwordx4 v[222:223], off
	v_mul_f32_e32 v226, 0xbfb8aa3b, v60
	v_mul_f32_e32 v227, 0xbfb8aa3b, v61
	v_mul_f32_e32 v228, 0xbfb8aa3b, v62
	v_mul_f32_e32 v229, 0xbfb8aa3b, v63
	v_exp_f32_e32 v226, v226
	v_exp_f32_e32 v227, v227
	v_exp_f32_e32 v228, v228
	v_exp_f32_e32 v229, v229
	v_add_f32_e32 v226, 1.0, v226
	v_add_f32_e32 v227, 1.0, v227
	v_add_f32_e32 v228, 1.0, v228
	v_add_f32_e32 v229, 1.0, v229
	v_rcp_f32_e32 v226, v226
	v_rcp_f32_e32 v227, v227
	v_rcp_f32_e32 v228, v228
	v_rcp_f32_e32 v229, v229
	v_mul_f32_e32 v226, v60, v226
	v_mul_f32_e32 v227, v61, v227
	v_mul_f32_e32 v228, v62, v228
	v_mul_f32_e32 v229, v63, v229
	v_mul_f32_e32 v52, v226, v52
	v_mul_f32_e32 v53, v227, v53
	v_mul_f32_e32 v54, v228, v54
	v_mul_f32_e32 v55, v229, v55
	v_mul_f32_e32 v226, 0xbfb8aa3b, v56
	v_mul_f32_e32 v227, 0xbfb8aa3b, v57
	v_mul_f32_e32 v228, 0xbfb8aa3b, v58
	v_mul_f32_e32 v229, 0xbfb8aa3b, v59
	v_exp_f32_e32 v226, v226
	v_exp_f32_e32 v227, v227
	v_exp_f32_e32 v228, v228
	v_exp_f32_e32 v229, v229
	v_add_f32_e32 v226, 1.0, v226
	v_add_f32_e32 v227, 1.0, v227
	v_add_f32_e32 v228, 1.0, v228
	v_add_f32_e32 v229, 1.0, v229
	v_rcp_f32_e32 v226, v226
	v_rcp_f32_e32 v227, v227
	v_rcp_f32_e32 v228, v228
	v_rcp_f32_e32 v229, v229
	v_mul_f32_e32 v226, v56, v226
	v_mul_f32_e32 v227, v57, v227
	v_mul_f32_e32 v228, v58, v228
	v_mul_f32_e32 v229, v59, v229
	v_mul_f32_e32 v48, v226, v48
	v_mul_f32_e32 v49, v227, v49
	v_mul_f32_e32 v50, v228, v50
	v_mul_f32_e32 v51, v229, v51
	v_cvt_pk_bf16_f32 v52, v52, v53
	v_cvt_pk_bf16_f32 v53, v54, v55
	v_cvt_pk_bf16_f32 v54, v48, v49
	v_cvt_pk_bf16_f32 v55, v50, v51
	v_add_u32_e32 v235, 0xb0000, v234
	s_nop 0
	global_store_dwordx4 v235, v[52:55], s[18:19] nt
	v_mul_f32_e32 v226, 0xbfb8aa3b, v44
	v_mul_f32_e32 v227, 0xbfb8aa3b, v45
	v_mul_f32_e32 v228, 0xbfb8aa3b, v46
	v_mul_f32_e32 v229, 0xbfb8aa3b, v47
	v_exp_f32_e32 v226, v226
	v_exp_f32_e32 v227, v227
	v_exp_f32_e32 v228, v228
	v_exp_f32_e32 v229, v229
	v_add_f32_e32 v226, 1.0, v226
	v_add_f32_e32 v227, 1.0, v227
	v_add_f32_e32 v228, 1.0, v228
	v_add_f32_e32 v229, 1.0, v229
	v_rcp_f32_e32 v226, v226
	v_rcp_f32_e32 v227, v227
	v_rcp_f32_e32 v228, v228
	v_rcp_f32_e32 v229, v229
	v_mul_f32_e32 v226, v44, v226
	v_mul_f32_e32 v227, v45, v227
	v_mul_f32_e32 v228, v46, v228
	v_mul_f32_e32 v229, v47, v229
	v_mul_f32_e32 v36, v226, v36
	v_mul_f32_e32 v37, v227, v37
	v_mul_f32_e32 v38, v228, v38
	v_mul_f32_e32 v39, v229, v39
	v_mul_f32_e32 v226, 0xbfb8aa3b, v40
	v_mul_f32_e32 v227, 0xbfb8aa3b, v41
	v_mul_f32_e32 v228, 0xbfb8aa3b, v42
	v_mul_f32_e32 v229, 0xbfb8aa3b, v43
	v_exp_f32_e32 v226, v226
	v_exp_f32_e32 v227, v227
	v_exp_f32_e32 v228, v228
	v_exp_f32_e32 v229, v229
	v_add_f32_e32 v226, 1.0, v226
	v_add_f32_e32 v227, 1.0, v227
	v_add_f32_e32 v228, 1.0, v228
	v_add_f32_e32 v229, 1.0, v229
	v_rcp_f32_e32 v226, v226
	v_rcp_f32_e32 v227, v227
	v_rcp_f32_e32 v228, v228
	v_rcp_f32_e32 v229, v229
	v_mul_f32_e32 v226, v40, v226
	v_mul_f32_e32 v227, v41, v227
	v_mul_f32_e32 v228, v42, v228
	v_mul_f32_e32 v229, v43, v229
	v_mul_f32_e32 v32, v226, v32
	v_mul_f32_e32 v33, v227, v33
	v_mul_f32_e32 v34, v228, v34
	v_mul_f32_e32 v35, v229, v35
	v_cvt_pk_bf16_f32 v36, v36, v37
	v_cvt_pk_bf16_f32 v37, v38, v39
	v_cvt_pk_bf16_f32 v38, v32, v33
	v_cvt_pk_bf16_f32 v39, v34, v35
	v_add_u32_e32 v235, 0xc6000, v234
	s_nop 0
	global_store_dwordx4 v235, v[36:39], s[18:19] nt
	v_mul_f32_e32 v226, 0xbfb8aa3b, v28
	v_mul_f32_e32 v227, 0xbfb8aa3b, v29
	v_mul_f32_e32 v228, 0xbfb8aa3b, v30
	v_mul_f32_e32 v229, 0xbfb8aa3b, v31
	v_exp_f32_e32 v226, v226
	v_exp_f32_e32 v227, v227
	v_exp_f32_e32 v228, v228
	v_exp_f32_e32 v229, v229
	v_add_f32_e32 v226, 1.0, v226
	v_add_f32_e32 v227, 1.0, v227
	v_add_f32_e32 v228, 1.0, v228
	v_add_f32_e32 v229, 1.0, v229
	v_rcp_f32_e32 v226, v226
	v_rcp_f32_e32 v227, v227
	v_rcp_f32_e32 v228, v228
	v_rcp_f32_e32 v229, v229
	v_mul_f32_e32 v226, v28, v226
	v_mul_f32_e32 v227, v29, v227
	v_mul_f32_e32 v228, v30, v228
	v_mul_f32_e32 v229, v31, v229
	v_mul_f32_e32 v20, v226, v20
	v_mul_f32_e32 v21, v227, v21
	v_mul_f32_e32 v22, v228, v22
	v_mul_f32_e32 v23, v229, v23
	v_mul_f32_e32 v226, 0xbfb8aa3b, v24
	v_mul_f32_e32 v227, 0xbfb8aa3b, v25
	v_mul_f32_e32 v228, 0xbfb8aa3b, v26
	v_mul_f32_e32 v229, 0xbfb8aa3b, v27
	v_exp_f32_e32 v226, v226
	v_exp_f32_e32 v227, v227
	v_exp_f32_e32 v228, v228
	v_exp_f32_e32 v229, v229
	v_add_f32_e32 v226, 1.0, v226
	v_add_f32_e32 v227, 1.0, v227
	v_add_f32_e32 v228, 1.0, v228
	v_add_f32_e32 v229, 1.0, v229
	v_rcp_f32_e32 v226, v226
; __device__ __forceinline__ unsigned cvt_pk_bf16(float lo, float hi) { unsigned r; asm volatile("v_cvt_pk_bf16_f32 %0, %1, %2" : "=v"(r) : "v"(lo), "v"(hi)); return r; }
; __device__ __forceinline__ float sigm(float x) { return __builtin_amdgcn_rcpf(1.0f + __builtin_amdgcn_exp2f(-1.4426950408889634f * x)); }
; #define PG8_STAGE(bufoff, gbase, voff) do { _Pragma("unroll") for (int _i = 0; _i < 2; ++_i) \
;         __builtin_amdgcn_global_load_lds((const unsigned*)((const char*)(gbase) + (voff)[_i]), (PG8_LAS unsigned*)(lds + (bufoff) + ldsw + _i * 8192), 16, 0, 0); } while (0)
; #define PG8_LDA(dst, b, h) do { _Pragma("unroll") for (int m = 0; m < 4; ++m) _Pragma("unroll") for (int k = 0; k < 2; ++k) dst[m][k] = *(const PG8_LAS bf16x8*)(lds + PG8_SA(b, h) + aoff + m * 2048 + k * 1024); } while (0)
;     __device__ __forceinline__ void operator()(const f32x4 (&acc)[2][2][4][2], const Unit& u, int wr, int wc, int fr, int fq) const {
;         const int row0 = u.pm * BM + wr * 64 + fr, col0 = u.pn * 128 + wc * 32 + 8 * fq;
; #pragma unroll
;         for (int ai = 0; ai < 2; ++ai)
; #pragma unroll
;             for (int m = 0; m < 4; ++m) { bf16_t* rowp = out + (size_t)(row0 + ai * HALF + m * 16) * 2816 + col0;
;                 const f32x4 g0 = acc[ai][0][m][0], g1 = acc[ai][0][m][1], u0 = acc[ai][1][m][0], u1 = acc[ai][1][m][1];
;                 u32x4 w;
;                 w.x = cvt_pk_bf16(g0[0] * sigm(g0[0]) * u0[0], g0[1] * sigm(g0[1]) * u0[1]);
;                 w.y = cvt_pk_bf16(g0[2] * sigm(g0[2]) * u0[2], g0[3] * sigm(g0[3]) * u0[3]);
;                 w.z = cvt_pk_bf16(g1[0] * sigm(g1[0]) * u1[0], g1[1] * sigm(g1[1]) * u1[1]);
;                 w.w = cvt_pk_bf16(g1[2] * sigm(g1[2]) * u1[2], g1[3] * sigm(g1[3]) * u1[3]);
;                 __builtin_nontemporal_store(w, (u32x4*)rowp); }
; template <class Epi, class Sched, bool ALIGN_EPI = false, bool SP2 = false>
; __device__ __forceinline__ void gemm_phase(PG8_LAS unsigned char* lds, const Gemm g, const Sched& S, const Epi& E) {
;     ...
;             PG8_WAIT_V(8); PG8_WAIT_L(0); PG8_BAR; PG8_MMA(1, 0, At, B0); PG8_MMA(1, 1, At, B1); PG8_BAR; PG8_SCHED;
;             PG8_LDB(B0, 1, 0); PG8_LDB(B1, 1, 1); PG8_SCHED; PG8_LDA(At, 1, 0); PG8_STAGE(PG8_SA(0, 1), a2 + hstepA, voffA);
;             PG8_WAIT_V(8); PG8_WAIT_L(0); PG8_BAR; PG8_MMA(0, 0, At, B0); PG8_MMA(0, 1, At, B1); PG8_BAR; PG8_SCHED;
	v_rcp_f32_e32 v227, v227
	v_rcp_f32_e32 v228, v228
	v_rcp_f32_e32 v229, v229
	v_mul_f32_e32 v226, v24, v226
	v_mul_f32_e32 v227, v25, v227
	v_mul_f32_e32 v228, v26, v228
	v_mul_f32_e32 v229, v27, v229
	v_mul_f32_e32 v16, v226, v16
	v_mul_f32_e32 v17, v227, v17
	v_mul_f32_e32 v18, v228, v18
	v_mul_f32_e32 v19, v229, v19
	v_cvt_pk_bf16_f32 v20, v20, v21
	v_cvt_pk_bf16_f32 v21, v22, v23
	v_cvt_pk_bf16_f32 v22, v16, v17
	v_cvt_pk_bf16_f32 v23, v18, v19
	v_add_u32_e32 v235, 0xdc000, v234
	s_nop 0
	global_store_dwordx4 v235, v[20:23], s[18:19] nt
	v_mul_f32_e32 v226, 0xbfb8aa3b, v12
	v_mul_f32_e32 v227, 0xbfb8aa3b, v13
	v_mul_f32_e32 v228, 0xbfb8aa3b, v14
	v_mul_f32_e32 v229, 0xbfb8aa3b, v15
	v_exp_f32_e32 v226, v226
	v_exp_f32_e32 v227, v227
	v_exp_f32_e32 v228, v228
	v_exp_f32_e32 v229, v229
	v_add_f32_e32 v226, 1.0, v226
	v_add_f32_e32 v227, 1.0, v227
	v_add_f32_e32 v228, 1.0, v228
	v_add_f32_e32 v229, 1.0, v229
	v_rcp_f32_e32 v226, v226
	v_rcp_f32_e32 v227, v227
	v_rcp_f32_e32 v228, v228
	v_rcp_f32_e32 v229, v229
	v_mul_f32_e32 v226, v12, v226
	v_mul_f32_e32 v227, v13, v227
	v_mul_f32_e32 v228, v14, v228
	v_mul_f32_e32 v229, v15, v229
	v_mul_f32_e32 v4, v226, v4
	v_mul_f32_e32 v5, v227, v5
	v_mul_f32_e32 v6, v228, v6
	v_mul_f32_e32 v7, v229, v7
	v_mul_f32_e32 v226, 0xbfb8aa3b, v8
	v_mul_f32_e32 v227, 0xbfb8aa3b, v9
	v_mul_f32_e32 v228, 0xbfb8aa3b, v10
	v_mul_f32_e32 v229, 0xbfb8aa3b, v11
	v_exp_f32_e32 v226, v226
	v_exp_f32_e32 v227, v227
	v_exp_f32_e32 v228, v228
	v_exp_f32_e32 v229, v229
	v_add_f32_e32 v226, 1.0, v226
	v_add_f32_e32 v227, 1.0, v227
	v_add_f32_e32 v228, 1.0, v228
	v_add_f32_e32 v229, 1.0, v229
	v_rcp_f32_e32 v226, v226
	v_rcp_f32_e32 v227, v227
	v_rcp_f32_e32 v228, v228
	v_rcp_f32_e32 v229, v229
	v_mul_f32_e32 v226, v8, v226
	v_mul_f32_e32 v227, v9, v227
	v_mul_f32_e32 v228, v10, v228
	v_mul_f32_e32 v229, v11, v229
	v_mul_f32_e32 v0, v226, v0
	v_mul_f32_e32 v1, v227, v1
	v_mul_f32_e32 v2, v228, v2
	v_mul_f32_e32 v3, v229, v3
	v_cvt_pk_bf16_f32 v4, v4, v5
	v_cvt_pk_bf16_f32 v5, v6, v7
	v_cvt_pk_bf16_f32 v6, v0, v1
	v_cvt_pk_bf16_f32 v7, v2, v3
	v_add_u32_e32 v235, 0xf2000, v234
	s_nop 0
	global_store_dwordx4 v235, v[4:7], s[18:19] nt
	s_waitcnt vmcnt(16)
	s_waitcnt lgkmcnt(0)
	s_barrier
	s_setprio 1
	s_waitcnt lgkmcnt(0)
	v_mfma_f32_16x16x32_bf16 v[60:63], v[144:147], v[184:187], 0
	v_mfma_f32_16x16x32_bf16 v[56:59], v[158:161], v[184:187], 0
	v_mfma_f32_16x16x32_bf16 v[44:47], v[144:147], v[192:195], 0
	v_mfma_f32_16x16x32_bf16 v[40:43], v[158:161], v[192:195], 0
	v_mfma_f32_16x16x32_bf16 v[28:31], v[144:147], v[200:203], 0
	v_mfma_f32_16x16x32_bf16 v[24:27], v[158:161], v[200:203], 0
	v_mfma_f32_16x16x32_bf16 v[12:15], v[144:147], v[208:211], 0
	v_mfma_f32_16x16x32_bf16 v[8:11], v[158:161], v[208:211], 0
	v_mfma_f32_16x16x32_bf16 v[60:63], v[154:157], v[188:191], v[60:63]
	v_mfma_f32_16x16x32_bf16 v[56:59], v[162:165], v[188:191], v[56:59]
	v_mfma_f32_16x16x32_bf16 v[44:47], v[154:157], v[196:199], v[44:47]
	v_mfma_f32_16x16x32_bf16 v[40:43], v[162:165], v[196:199], v[40:43]
	v_mfma_f32_16x16x32_bf16 v[28:31], v[154:157], v[204:207], v[28:31]
	v_mfma_f32_16x16x32_bf16 v[24:27], v[162:165], v[204:207], v[24:27]
	v_mfma_f32_16x16x32_bf16 v[12:15], v[154:157], v[212:215], v[12:15]
	v_mfma_f32_16x16x32_bf16 v[8:11], v[162:165], v[212:215], v[8:11]
	s_setprio 0
	s_setprio 1
	v_mfma_f32_16x16x32_bf16 v[52:55], v[166:169], v[184:187], 0
	v_mfma_f32_16x16x32_bf16 v[48:51], v[176:179], v[184:187], 0
	v_mfma_f32_16x16x32_bf16 v[36:39], v[166:169], v[192:195], 0
	v_mfma_f32_16x16x32_bf16 v[32:35], v[176:179], v[192:195], 0
	v_mfma_f32_16x16x32_bf16 v[20:23], v[166:169], v[200:203], 0
	v_mfma_f32_16x16x32_bf16 v[16:19], v[176:179], v[200:203], 0
	v_mfma_f32_16x16x32_bf16 v[4:7], v[166:169], v[208:211], 0
	v_mfma_f32_16x16x32_bf16 v[0:3], v[176:179], v[208:211], 0
	v_mfma_f32_16x16x32_bf16 v[52:55], v[170:173], v[188:191], v[52:55]
	v_mfma_f32_16x16x32_bf16 v[48:51], v[180:183], v[188:191], v[48:51]
	v_mfma_f32_16x16x32_bf16 v[36:39], v[170:173], v[196:199], v[36:39]
	v_mfma_f32_16x16x32_bf16 v[32:35], v[180:183], v[196:199], v[32:35]
	v_mfma_f32_16x16x32_bf16 v[20:23], v[170:173], v[204:207], v[20:23]
	v_mfma_f32_16x16x32_bf16 v[16:19], v[180:183], v[204:207], v[16:19]
	v_mfma_f32_16x16x32_bf16 v[4:7], v[170:173], v[212:215], v[4:7]
	v_mfma_f32_16x16x32_bf16 v[0:3], v[180:183], v[212:215], v[0:3]
	s_setprio 0
	s_barrier
	s_add_i32 s33, 0, 0x18000
	s_add_i32 s57, 0, 0x1c000
	v_add_u32_e32 v162, s33, v149
	v_add_u32_e32 v175, s57, v149
	ds_read_b128 v[144:147], v162
	ds_read_b128 v[154:157], v162 offset:1024
	ds_read_b128 v[158:161], v162 offset:2048
	ds_read_b128 v[162:165], v162 offset:3072
	ds_read_b128 v[166:169], v175
	ds_read_b128 v[170:173], v175 offset:1024
	ds_read_b128 v[176:179], v175 offset:2048
	ds_read_b128 v[180:183], v175 offset:3072
	s_add_u32 s42, s42, 0x40000
	s_addc_u32 s43, s43, 0
	s_mov_b32 m0, s31
	v_lshl_add_u64 v[224:225], s[42:43], 0, v[134:135]
	ds_read_b128 v[184:187], v153 offset:32768
	ds_read_b128 v[188:191], v153 offset:33792
	ds_read_b128 v[192:195], v153 offset:34816
	ds_read_b128 v[196:199], v153 offset:35840
	ds_read_b128 v[200:203], v153 offset:36864
	ds_read_b128 v[204:207], v153 offset:37888
	ds_read_b128 v[208:211], v153 offset:38912
	ds_read_b128 v[212:215], v153 offset:39936
	global_load_lds_dwordx4 v[224:225], off
	v_lshl_add_u64 v[224:225], s[42:43], 0, v[130:131]
	s_mov_b32 m0, s35
	s_nop 0
	global_load_lds_dwordx4 v[224:225], off
	s_waitcnt vmcnt(16)
	s_waitcnt lgkmcnt(0)
	s_barrier
; #define PG8_STAGE(bufoff, gbase, voff) do { _Pragma("unroll") for (int _i = 0; _i < 2; ++_i) \
;         __builtin_amdgcn_global_load_lds((const unsigned*)((const char*)(gbase) + (voff)[_i]), (PG8_LAS unsigned*)(lds + (bufoff) + ldsw + _i * 8192), 16, 0, 0); } while (0)
; #define PG8_LDA(dst, b, h) do { _Pragma("unroll") for (int m = 0; m < 4; ++m) _Pragma("unroll") for (int k = 0; k < 2; ++k) dst[m][k] = *(const PG8_LAS bf16x8*)(lds + PG8_SA(b, h) + aoff + m * 2048 + k * 1024); } while (0)
; #define PG8_LDB(dst, b, h) do { _Pragma("unroll") for (int n = 0; n < 2; ++n) _Pragma("unroll") for (int k = 0; k < 2; ++k) dst[n][k] = *(const PG8_LAS bf16x8*)(lds + PG8_SB(b, h) + boff + n * 2048 + k * 1024); } while (0)
; #define PG8_MMA(ai, bj, At, Bt) do { __builtin_amdgcn_s_setprio(1); _Pragma("unroll") for (int m = 0; m < 4; ++m) _Pragma("unroll") for (int n = 0; n < 2; ++n) _Pragma("unroll") for (int k = 0; k < 2; ++k) \
;         acc[ai][bj][m][n] = __builtin_amdgcn_mfma_f32_16x16x32_bf16(Bt[n][k], At[m][k], acc[ai][bj][m][n], 0, 0, 0); __builtin_amdgcn_s_setprio(0); } while (0)
; #define PG8_WAIT_V(n) asm volatile("s_waitcnt vmcnt(" #n ")" ::: "memory")
; #define PG8_WAIT_L(n) asm volatile("s_waitcnt lgkmcnt(" #n ")" ::: "memory")
; #define PG8_BAR __builtin_amdgcn_s_barrier()
; #define PG8_SCHED __builtin_amdgcn_sched_barrier(0)
; template <class Epi, class Sched, bool ALIGN_EPI = false, bool SP2 = false>
; __device__ __forceinline__ void gemm_phase(PG8_LAS unsigned char* lds, const Gemm g, const Sched& S, const Epi& E) {
;     ...
;             PG8_LDB(B0, 1, 0); PG8_LDB(B1, 1, 1); PG8_SCHED; PG8_LDA(At, 1, 0); PG8_STAGE(PG8_SA(0, 1), a2 + hstepA, voffA);
;             PG8_WAIT_V(8); PG8_WAIT_L(0); PG8_BAR; PG8_MMA(0, 0, At, B0); PG8_MMA(0, 1, At, B1); PG8_BAR; PG8_SCHED;
;             PG8_LDA(At, 1, 1); PG8_STAGE(PG8_SB(1, 0), b3, voffB); PG8_STAGE(PG8_SB(1, 1), b3 + hstepB, voffB); PG8_STAGE(PG8_SA(1, 0), a3, voffA);
;             PG8_WAIT_V(8); PG8_WAIT_L(0); PG8_BAR; PG8_MMA(1, 0, At, B0); PG8_MMA(1, 1, At, B1); PG8_BAR; PG8_SCHED;
	s_setprio 1
	s_waitcnt lgkmcnt(0)
	v_mfma_f32_16x16x32_bf16 v[124:127], v[144:147], v[184:187], v[124:127]
	v_mfma_f32_16x16x32_bf16 v[120:123], v[158:161], v[184:187], v[120:123]
	v_mfma_f32_16x16x32_bf16 v[108:111], v[144:147], v[192:195], v[108:111]
	v_mfma_f32_16x16x32_bf16 v[104:107], v[158:161], v[192:195], v[104:107]
	v_mfma_f32_16x16x32_bf16 v[92:95], v[144:147], v[200:203], v[92:95]
	v_mfma_f32_16x16x32_bf16 v[88:91], v[158:161], v[200:203], v[88:91]
	v_mfma_f32_16x16x32_bf16 v[76:79], v[144:147], v[208:211], v[76:79]
	v_mfma_f32_16x16x32_bf16 v[72:75], v[158:161], v[208:211], v[72:75]
	v_mfma_f32_16x16x32_bf16 v[124:127], v[154:157], v[188:191], v[124:127]
	v_mfma_f32_16x16x32_bf16 v[120:123], v[162:165], v[188:191], v[120:123]
	v_mfma_f32_16x16x32_bf16 v[108:111], v[154:157], v[196:199], v[108:111]
	v_mfma_f32_16x16x32_bf16 v[104:107], v[162:165], v[196:199], v[104:107]
	v_mfma_f32_16x16x32_bf16 v[92:95], v[154:157], v[204:207], v[92:95]
	v_mfma_f32_16x16x32_bf16 v[88:91], v[162:165], v[204:207], v[88:91]
	v_mfma_f32_16x16x32_bf16 v[76:79], v[154:157], v[212:215], v[76:79]
	v_mfma_f32_16x16x32_bf16 v[72:75], v[162:165], v[212:215], v[72:75]
	s_setprio 0
	s_setprio 1
	v_mfma_f32_16x16x32_bf16 v[116:119], v[166:169], v[184:187], v[116:119]
	v_mfma_f32_16x16x32_bf16 v[112:115], v[176:179], v[184:187], v[112:115]
	v_mfma_f32_16x16x32_bf16 v[100:103], v[166:169], v[192:195], v[100:103]
	v_mfma_f32_16x16x32_bf16 v[96:99], v[176:179], v[192:195], v[96:99]
	v_mfma_f32_16x16x32_bf16 v[84:87], v[166:169], v[200:203], v[84:87]
	v_mfma_f32_16x16x32_bf16 v[80:83], v[176:179], v[200:203], v[80:83]
	v_mfma_f32_16x16x32_bf16 v[68:71], v[166:169], v[208:211], v[68:71]
	v_mfma_f32_16x16x32_bf16 v[64:67], v[176:179], v[208:211], v[64:67]
	v_mfma_f32_16x16x32_bf16 v[116:119], v[170:173], v[188:191], v[116:119]
	v_mfma_f32_16x16x32_bf16 v[112:115], v[180:183], v[188:191], v[112:115]
	v_mfma_f32_16x16x32_bf16 v[100:103], v[170:173], v[196:199], v[100:103]
	v_mfma_f32_16x16x32_bf16 v[96:99], v[180:183], v[196:199], v[96:99]
	v_mfma_f32_16x16x32_bf16 v[84:87], v[170:173], v[204:207], v[84:87]
	v_mfma_f32_16x16x32_bf16 v[80:83], v[180:183], v[204:207], v[80:83]
	v_mfma_f32_16x16x32_bf16 v[68:71], v[170:173], v[212:215], v[68:71]
	v_mfma_f32_16x16x32_bf16 v[64:67], v[180:183], v[212:215], v[64:67]
	s_setprio 0
	s_barrier
	s_add_i32 s33, s33, s22
	v_lshl_add_u64 v[216:217], v[216:217], 0, s[6:7]
	s_mov_b32 m0, s33
	ds_read_b128 v[184:187], v153 offset:49152
	ds_read_b128 v[188:191], v153 offset:50176
	ds_read_b128 v[192:195], v153 offset:51200
	ds_read_b128 v[196:199], v153 offset:52224
	ds_read_b128 v[200:203], v153 offset:53248
	ds_read_b128 v[204:207], v153 offset:54272
	ds_read_b128 v[208:211], v153 offset:55296
	ds_read_b128 v[212:215], v153 offset:56320
	global_load_lds_dwordx4 v[216:217], off
	s_add_i32 m0, s33, 0x2000
	s_add_u32 s40, s40, 0x40080
	v_lshl_add_u64 v[216:217], v[218:219], 0, s[6:7]
	s_addc_u32 s41, s41, 0
	s_add_i32 s33, s57, s22
	global_load_lds_dwordx4 v[216:217], off
	v_lshl_add_u64 v[216:217], s[40:41], 0, v[132:133]
	s_mov_b32 m0, s33
	s_nop 0
	global_load_lds_dwordx4 v[216:217], off
	v_lshl_add_u64 v[216:217], s[40:41], 0, v[128:129]
	s_add_i32 m0, s33, 0x2000
	s_nop 0
	global_load_lds_dwordx4 v[216:217], off
	v_lshl_add_u64 v[216:217], v[220:221], 0, s[6:7]
	s_mov_b32 m0, s44
	s_nop 0
	global_load_lds_dwordx4 v[216:217], off
	v_lshl_add_u64 v[216:217], v[222:223], 0, s[6:7]
	s_mov_b32 m0, s45
	s_nop 0
	global_load_lds_dwordx4 v[216:217], off
	s_waitcnt vmcnt(12)
	s_waitcnt lgkmcnt(0)
	s_barrier
	s_setprio 1
	s_waitcnt lgkmcnt(0)
	v_mfma_f32_16x16x32_bf16 v[60:63], v[144:147], v[184:187], v[60:63]
	v_mfma_f32_16x16x32_bf16 v[56:59], v[158:161], v[184:187], v[56:59]
	v_mfma_f32_16x16x32_bf16 v[44:47], v[144:147], v[192:195], v[44:47]
	v_mfma_f32_16x16x32_bf16 v[40:43], v[158:161], v[192:195], v[40:43]
	v_mfma_f32_16x16x32_bf16 v[28:31], v[144:147], v[200:203], v[28:31]
	v_mfma_f32_16x16x32_bf16 v[24:27], v[158:161], v[200:203], v[24:27]
	v_mfma_f32_16x16x32_bf16 v[12:15], v[144:147], v[208:211], v[12:15]
	v_mfma_f32_16x16x32_bf16 v[8:11], v[158:161], v[208:211], v[8:11]
	v_mfma_f32_16x16x32_bf16 v[60:63], v[154:157], v[188:191], v[60:63]
	v_mfma_f32_16x16x32_bf16 v[56:59], v[162:165], v[188:191], v[56:59]
	v_mfma_f32_16x16x32_bf16 v[44:47], v[154:157], v[196:199], v[44:47]
	v_mfma_f32_16x16x32_bf16 v[40:43], v[162:165], v[196:199], v[40:43]
	v_mfma_f32_16x16x32_bf16 v[28:31], v[154:157], v[204:207], v[28:31]
	v_mfma_f32_16x16x32_bf16 v[24:27], v[162:165], v[204:207], v[24:27]
	v_mfma_f32_16x16x32_bf16 v[12:15], v[154:157], v[212:215], v[12:15]
	v_mfma_f32_16x16x32_bf16 v[8:11], v[162:165], v[212:215], v[8:11]
	s_setprio 0
	s_setprio 1
	v_mfma_f32_16x16x32_bf16 v[52:55], v[166:169], v[184:187], v[52:55]
	v_mfma_f32_16x16x32_bf16 v[48:51], v[176:179], v[184:187], v[48:51]
	v_mfma_f32_16x16x32_bf16 v[36:39], v[166:169], v[192:195], v[36:39]
	v_mfma_f32_16x16x32_bf16 v[32:35], v[176:179], v[192:195], v[32:35]
	v_mfma_f32_16x16x32_bf16 v[20:23], v[166:169], v[200:203], v[20:23]
	v_mfma_f32_16x16x32_bf16 v[16:19], v[176:179], v[200:203], v[16:19]
	v_mfma_f32_16x16x32_bf16 v[4:7], v[166:169], v[208:211], v[4:7]
	v_mfma_f32_16x16x32_bf16 v[0:3], v[176:179], v[208:211], v[0:3]
	v_mfma_f32_16x16x32_bf16 v[52:55], v[170:173], v[188:191], v[52:55]
	v_mfma_f32_16x16x32_bf16 v[48:51], v[180:183], v[188:191], v[48:51]
	v_mfma_f32_16x16x32_bf16 v[36:39], v[170:173], v[196:199], v[36:39]
	v_mfma_f32_16x16x32_bf16 v[32:35], v[180:183], v[196:199], v[32:35]
	v_mfma_f32_16x16x32_bf16 v[20:23], v[170:173], v[204:207], v[20:23]
	v_mfma_f32_16x16x32_bf16 v[16:19], v[180:183], v[204:207], v[16:19]
	v_mfma_f32_16x16x32_bf16 v[4:7], v[170:173], v[212:215], v[4:7]
	v_mfma_f32_16x16x32_bf16 v[0:3], v[180:183], v[212:215], v[0:3]
	s_setprio 0
	s_barrier
	s_add_i32 s56, s56, 2
	s_add_u32 s38, s38, 0x100
	s_addc_u32 s39, s39, 0
	s_add_u32 s54, s54, 0x100
	s_addc_u32 s55, s55, 0
	s_cmp_gt_u32 s56, 13
	s_branch .LBB0_605
